# GEMM K-loops: 48 LDS-DMA pieces use scalar-base + 32-bit lane offset addressing (global_load_lds vOff, sBase) instead of a 64-bit VALU add + VGPR-pair address
# baseline (speedup 1.0000x reference)
.LBB0_226:
	s_add_i32 vcc_lo, s82, 2
	s_add_u32 s20, s66, 0xffff0080
	s_addc_u32 s21, s67, -1
	s_add_i32 s52, 0, 0x10000
	s_cmp_eq_u32 s60, s82
	s_cselect_b32 s87, s39, s21
	s_cselect_b32 s86, s41, s20
	s_cselect_b32 s83, s88, s95
	s_cselect_b32 s82, s89, s94
	s_add_i32 s53, 0, 0x14000
	v_add_u32_e32 v154, s52, v140
	v_add_u32_e32 v170, s53, v140
	ds_read_b128 v[142:145], v154
	ds_read_b128 v[146:149], v154 offset:1024
	ds_read_b128 v[150:153], v154 offset:2048
	ds_read_b128 v[154:157], v154 offset:3072
	ds_read_b128 v[158:161], v170
	ds_read_b128 v[162:165], v170 offset:1024
	ds_read_b128 v[166:169], v170 offset:2048
	ds_read_b128 v[170:173], v170 offset:3072
	s_add_i32 m0, s13, 0xc000
	ds_read_b128 v[174:177], v141
	ds_read_b128 v[178:181], v141 offset:1024
	ds_read_b128 v[182:185], v141 offset:2048
	ds_read_b128 v[202:205], v141 offset:3072
	ds_read_b128 v[216:219], v141 offset:4096
	ds_read_b128 v[220:223], v141 offset:5120
	ds_read_b128 v[224:227], v141 offset:6144
	ds_read_b128 v[228:231], v141 offset:7168
	global_load_lds_dwordx4 v134, s[66:67]
	s_add_i32 m0, s13, 0xe000
	s_nop 0
	global_load_lds_dwordx4 v136, s[66:67]
	s_waitcnt vmcnt(8)
	s_waitcnt lgkmcnt(0)
	s_barrier
	s_setprio 1
	s_waitcnt lgkmcnt(0)
	v_mfma_f32_16x16x32_bf16 v[120:123], v[142:145], v[174:177], v[120:123]
	v_mfma_f32_16x16x32_bf16 v[124:127], v[150:153], v[174:177], v[124:127]
	v_mfma_f32_16x16x32_bf16 v[108:111], v[142:145], v[182:185], v[108:111]
	v_mfma_f32_16x16x32_bf16 v[104:107], v[150:153], v[182:185], v[104:107]
	v_mfma_f32_16x16x32_bf16 v[92:95], v[142:145], v[216:219], v[92:95]
	v_mfma_f32_16x16x32_bf16 v[88:91], v[150:153], v[216:219], v[88:91]
	v_mfma_f32_16x16x32_bf16 v[76:79], v[142:145], v[224:227], v[76:79]
	v_mfma_f32_16x16x32_bf16 v[72:75], v[150:153], v[224:227], v[72:75]
	v_mfma_f32_16x16x32_bf16 v[120:123], v[146:149], v[178:181], v[120:123]
	v_mfma_f32_16x16x32_bf16 v[124:127], v[154:157], v[178:181], v[124:127]
	v_mfma_f32_16x16x32_bf16 v[108:111], v[146:149], v[202:205], v[108:111]
	v_mfma_f32_16x16x32_bf16 v[104:107], v[154:157], v[202:205], v[104:107]
	v_mfma_f32_16x16x32_bf16 v[92:95], v[146:149], v[220:223], v[92:95]
	v_mfma_f32_16x16x32_bf16 v[88:91], v[154:157], v[220:223], v[88:91]
	v_mfma_f32_16x16x32_bf16 v[76:79], v[146:149], v[228:231], v[76:79]
	v_mfma_f32_16x16x32_bf16 v[72:75], v[154:157], v[228:231], v[72:75]
	s_setprio 0
	s_setprio 1
	v_mfma_f32_16x16x32_bf16 v[116:119], v[158:161], v[174:177], v[116:119]
	v_mfma_f32_16x16x32_bf16 v[112:115], v[166:169], v[174:177], v[112:115]
	v_mfma_f32_16x16x32_bf16 v[100:103], v[158:161], v[182:185], v[100:103]
	v_mfma_f32_16x16x32_bf16 v[96:99], v[166:169], v[182:185], v[96:99]
	v_mfma_f32_16x16x32_bf16 v[84:87], v[158:161], v[216:219], v[84:87]
	v_mfma_f32_16x16x32_bf16 v[80:83], v[166:169], v[216:219], v[80:83]
	v_mfma_f32_16x16x32_bf16 v[68:71], v[158:161], v[224:227], v[68:71]
	v_mfma_f32_16x16x32_bf16 v[64:67], v[166:169], v[224:227], v[64:67]
	v_mfma_f32_16x16x32_bf16 v[116:119], v[162:165], v[178:181], v[116:119]
	v_mfma_f32_16x16x32_bf16 v[112:115], v[170:173], v[178:181], v[112:115]
	v_mfma_f32_16x16x32_bf16 v[100:103], v[162:165], v[202:205], v[100:103]
	v_mfma_f32_16x16x32_bf16 v[96:99], v[170:173], v[202:205], v[96:99]
	v_mfma_f32_16x16x32_bf16 v[84:87], v[162:165], v[220:223], v[84:87]
	v_mfma_f32_16x16x32_bf16 v[80:83], v[170:173], v[220:223], v[80:83]
	v_mfma_f32_16x16x32_bf16 v[68:71], v[162:165], v[228:231], v[68:71]
	v_mfma_f32_16x16x32_bf16 v[64:67], v[170:173], v[228:231], v[64:67]
	s_setprio 0
	s_barrier
	s_add_i32 s20, s52, s12
	v_lshl_add_u64 v[186:187], s[82:83], 0, v[188:189]
	s_mov_b32 m0, s20
	ds_read_b128 v[174:177], v141 offset:16384
	ds_read_b128 v[178:181], v141 offset:17408
	ds_read_b128 v[182:185], v141 offset:18432
	ds_read_b128 v[202:205], v141 offset:19456
	ds_read_b128 v[216:219], v141 offset:20480
	ds_read_b128 v[220:223], v141 offset:21504
	ds_read_b128 v[224:227], v141 offset:22528
	ds_read_b128 v[228:231], v141 offset:23552
	global_load_lds_dwordx4 v[186:187], off
	s_add_i32 m0, s20, 0x2000
	s_add_u32 s20, s82, 0x10000
	v_lshl_add_u64 v[194:195], s[82:83], 0, v[128:129]
	s_addc_u32 s21, s83, 0
	s_add_i32 s52, s53, s12
	global_load_lds_dwordx4 v[194:195], off
	s_mov_b32 m0, s52
	v_lshl_add_u64 v[232:233], s[86:87], 0, v[130:131]
	global_load_lds_dwordx4 v188, s[20:21]
	s_add_i32 m0, s52, 0x2000
	s_nop 0
	global_load_lds_dwordx4 v128, s[20:21]
	v_lshl_add_u64 v[196:197], s[86:87], 0, v[132:133]
	s_mov_b32 m0, s13
	s_nop 0
	global_load_lds_dwordx4 v[196:197], off
	s_mov_b32 m0, s28
	s_nop 0
	global_load_lds_dwordx4 v[232:233], off
	s_waitcnt vmcnt(8)
	s_waitcnt lgkmcnt(0)
	s_barrier
	s_setprio 1
	s_waitcnt lgkmcnt(0)
	v_mfma_f32_16x16x32_bf16 v[60:63], v[142:145], v[174:177], v[60:63]
	v_mfma_f32_16x16x32_bf16 v[56:59], v[150:153], v[174:177], v[56:59]
	v_mfma_f32_16x16x32_bf16 v[44:47], v[142:145], v[182:185], v[44:47]
	v_mfma_f32_16x16x32_bf16 v[40:43], v[150:153], v[182:185], v[40:43]
	v_mfma_f32_16x16x32_bf16 v[28:31], v[142:145], v[216:219], v[28:31]
	v_mfma_f32_16x16x32_bf16 v[24:27], v[150:153], v[216:219], v[24:27]
	v_mfma_f32_16x16x32_bf16 v[12:15], v[142:145], v[224:227], v[12:15]
	v_mfma_f32_16x16x32_bf16 v[8:11], v[150:153], v[224:227], v[8:11]
	v_mfma_f32_16x16x32_bf16 v[60:63], v[146:149], v[178:181], v[60:63]
	v_mfma_f32_16x16x32_bf16 v[56:59], v[154:157], v[178:181], v[56:59]
	v_mfma_f32_16x16x32_bf16 v[44:47], v[146:149], v[202:205], v[44:47]
	v_mfma_f32_16x16x32_bf16 v[40:43], v[154:157], v[202:205], v[40:43]
	v_mfma_f32_16x16x32_bf16 v[28:31], v[146:149], v[220:223], v[28:31]
	v_mfma_f32_16x16x32_bf16 v[24:27], v[154:157], v[220:223], v[24:27]
	v_mfma_f32_16x16x32_bf16 v[12:15], v[146:149], v[228:231], v[12:15]
	v_mfma_f32_16x16x32_bf16 v[8:11], v[154:157], v[228:231], v[8:11]
	s_setprio 0
	s_setprio 1
	v_mfma_f32_16x16x32_bf16 v[52:55], v[158:161], v[174:177], v[52:55]
	v_mfma_f32_16x16x32_bf16 v[48:51], v[166:169], v[174:177], v[48:51]
	v_mfma_f32_16x16x32_bf16 v[36:39], v[158:161], v[182:185], v[36:39]
	v_mfma_f32_16x16x32_bf16 v[32:35], v[166:169], v[182:185], v[32:35]
	v_mfma_f32_16x16x32_bf16 v[20:23], v[158:161], v[216:219], v[20:23]
	v_mfma_f32_16x16x32_bf16 v[16:19], v[166:169], v[216:219], v[16:19]
	v_mfma_f32_16x16x32_bf16 v[4:7], v[158:161], v[224:227], v[4:7]
	v_mfma_f32_16x16x32_bf16 v[0:3], v[166:169], v[224:227], v[0:3]
	v_mfma_f32_16x16x32_bf16 v[52:55], v[162:165], v[178:181], v[52:55]
	v_mfma_f32_16x16x32_bf16 v[48:51], v[170:173], v[178:181], v[48:51]
	v_mfma_f32_16x16x32_bf16 v[36:39], v[162:165], v[202:205], v[36:39]
	v_mfma_f32_16x16x32_bf16 v[32:35], v[170:173], v[202:205], v[32:35]
	v_mfma_f32_16x16x32_bf16 v[20:23], v[162:165], v[220:223], v[20:23]
	v_mfma_f32_16x16x32_bf16 v[16:19], v[170:173], v[220:223], v[16:19]
	v_mfma_f32_16x16x32_bf16 v[4:7], v[162:165], v[228:231], v[4:7]
	v_mfma_f32_16x16x32_bf16 v[0:3], v[170:173], v[228:231], v[0:3]
	s_setprio 0
	s_barrier
	s_add_i32 s52, 0, 0x18000
	s_add_i32 s53, 0, 0x1c000
	v_add_u32_e32 v154, s52, v140
	v_add_u32_e32 v170, s53, v140
	ds_read_b128 v[142:145], v154
	ds_read_b128 v[146:149], v154 offset:1024
	ds_read_b128 v[150:153], v154 offset:2048
	ds_read_b128 v[154:157], v154 offset:3072
	ds_read_b128 v[158:161], v170
	ds_read_b128 v[162:165], v170 offset:1024
	ds_read_b128 v[166:169], v170 offset:2048
	ds_read_b128 v[170:173], v170 offset:3072
	s_add_u32 s20, s86, 0x10000
	s_addc_u32 s21, s87, 0
	s_mov_b32 m0, s46
	ds_read_b128 v[174:177], v141 offset:32768
	ds_read_b128 v[178:181], v141 offset:33792
	ds_read_b128 v[182:185], v141 offset:34816
	ds_read_b128 v[202:205], v141 offset:35840
	ds_read_b128 v[216:219], v141 offset:36864
	ds_read_b128 v[220:223], v141 offset:37888
	ds_read_b128 v[224:227], v141 offset:38912
	ds_read_b128 v[228:231], v141 offset:39936
	global_load_lds_dwordx4 v132, s[20:21]
	s_mov_b32 m0, s47
	s_nop 0
	global_load_lds_dwordx4 v130, s[20:21]
	s_waitcnt vmcnt(8)
	s_waitcnt lgkmcnt(0)
	s_barrier
	s_setprio 1
	s_waitcnt lgkmcnt(0)
	v_mfma_f32_16x16x32_bf16 v[120:123], v[142:145], v[174:177], v[120:123]
	v_mfma_f32_16x16x32_bf16 v[124:127], v[150:153], v[174:177], v[124:127]
	v_mfma_f32_16x16x32_bf16 v[108:111], v[142:145], v[182:185], v[108:111]
	v_mfma_f32_16x16x32_bf16 v[104:107], v[150:153], v[182:185], v[104:107]
	v_mfma_f32_16x16x32_bf16 v[92:95], v[142:145], v[216:219], v[92:95]
	v_mfma_f32_16x16x32_bf16 v[88:91], v[150:153], v[216:219], v[88:91]
	v_mfma_f32_16x16x32_bf16 v[76:79], v[142:145], v[224:227], v[76:79]
	v_mfma_f32_16x16x32_bf16 v[72:75], v[150:153], v[224:227], v[72:75]
	v_mfma_f32_16x16x32_bf16 v[120:123], v[146:149], v[178:181], v[120:123]
	v_mfma_f32_16x16x32_bf16 v[124:127], v[154:157], v[178:181], v[124:127]
	v_mfma_f32_16x16x32_bf16 v[108:111], v[146:149], v[202:205], v[108:111]
	v_mfma_f32_16x16x32_bf16 v[104:107], v[154:157], v[202:205], v[104:107]
	v_mfma_f32_16x16x32_bf16 v[92:95], v[146:149], v[220:223], v[92:95]
	v_mfma_f32_16x16x32_bf16 v[88:91], v[154:157], v[220:223], v[88:91]
	v_mfma_f32_16x16x32_bf16 v[76:79], v[146:149], v[228:231], v[76:79]
	v_mfma_f32_16x16x32_bf16 v[72:75], v[154:157], v[228:231], v[72:75]
	s_setprio 0
	s_setprio 1
	v_mfma_f32_16x16x32_bf16 v[116:119], v[158:161], v[174:177], v[116:119]
	v_mfma_f32_16x16x32_bf16 v[112:115], v[166:169], v[174:177], v[112:115]
	v_mfma_f32_16x16x32_bf16 v[100:103], v[158:161], v[182:185], v[100:103]
	v_mfma_f32_16x16x32_bf16 v[96:99], v[166:169], v[182:185], v[96:99]
	v_mfma_f32_16x16x32_bf16 v[84:87], v[158:161], v[216:219], v[84:87]
	v_mfma_f32_16x16x32_bf16 v[80:83], v[166:169], v[216:219], v[80:83]
	v_mfma_f32_16x16x32_bf16 v[68:71], v[158:161], v[224:227], v[68:71]
	v_mfma_f32_16x16x32_bf16 v[64:67], v[166:169], v[224:227], v[64:67]
	v_mfma_f32_16x16x32_bf16 v[116:119], v[162:165], v[178:181], v[116:119]
	v_mfma_f32_16x16x32_bf16 v[112:115], v[170:173], v[178:181], v[112:115]
	v_mfma_f32_16x16x32_bf16 v[100:103], v[162:165], v[202:205], v[100:103]
	v_mfma_f32_16x16x32_bf16 v[96:99], v[170:173], v[202:205], v[96:99]
	v_mfma_f32_16x16x32_bf16 v[84:87], v[162:165], v[220:223], v[84:87]
	v_mfma_f32_16x16x32_bf16 v[80:83], v[170:173], v[220:223], v[80:83]
	v_mfma_f32_16x16x32_bf16 v[68:71], v[162:165], v[228:231], v[68:71]
	v_mfma_f32_16x16x32_bf16 v[64:67], v[170:173], v[228:231], v[64:67]
	s_setprio 0
	s_barrier
	s_add_i32 s20, s52, s12
	v_lshl_add_u64 v[186:187], v[186:187], 0, s[62:63]
	s_mov_b32 m0, s20
	ds_read_b128 v[174:177], v141 offset:49152
	ds_read_b128 v[178:181], v141 offset:50176
	ds_read_b128 v[182:185], v141 offset:51200
	ds_read_b128 v[202:205], v141 offset:52224
	ds_read_b128 v[216:219], v141 offset:53248
	ds_read_b128 v[220:223], v141 offset:54272
	ds_read_b128 v[224:227], v141 offset:55296
	ds_read_b128 v[228:231], v141 offset:56320
	global_load_lds_dwordx4 v[186:187], off
	s_add_i32 m0, s20, 0x2000
	s_add_u32 s20, s82, 0x10080
	v_lshl_add_u64 v[186:187], v[194:195], 0, s[62:63]
	s_addc_u32 s21, s83, 0
	s_add_i32 s52, s53, s12
	global_load_lds_dwordx4 v[186:187], off
	s_mov_b32 m0, s52
	s_nop 0
	global_load_lds_dwordx4 v188, s[20:21]
	s_add_i32 m0, s52, 0x2000
	s_nop 0
	global_load_lds_dwordx4 v128, s[20:21]
	v_lshl_add_u64 v[186:187], v[196:197], 0, s[62:63]
	s_mov_b32 m0, s56
	s_nop 0
	global_load_lds_dwordx4 v[186:187], off
	v_lshl_add_u64 v[186:187], v[232:233], 0, s[62:63]
	s_mov_b32 m0, s57
	s_nop 0
	global_load_lds_dwordx4 v[186:187], off
	s_waitcnt vmcnt(8)
	s_waitcnt lgkmcnt(0)
	s_barrier
	s_setprio 1
	s_waitcnt lgkmcnt(0)
	v_mfma_f32_16x16x32_bf16 v[60:63], v[142:145], v[174:177], v[60:63]
	v_mfma_f32_16x16x32_bf16 v[56:59], v[150:153], v[174:177], v[56:59]
	v_mfma_f32_16x16x32_bf16 v[44:47], v[142:145], v[182:185], v[44:47]
	v_mfma_f32_16x16x32_bf16 v[40:43], v[150:153], v[182:185], v[40:43]
	v_mfma_f32_16x16x32_bf16 v[28:31], v[142:145], v[216:219], v[28:31]
	v_mfma_f32_16x16x32_bf16 v[24:27], v[150:153], v[216:219], v[24:27]
	v_mfma_f32_16x16x32_bf16 v[12:15], v[142:145], v[224:227], v[12:15]
	v_mfma_f32_16x16x32_bf16 v[8:11], v[150:153], v[224:227], v[8:11]
	v_mfma_f32_16x16x32_bf16 v[60:63], v[146:149], v[178:181], v[60:63]
	v_mfma_f32_16x16x32_bf16 v[56:59], v[154:157], v[178:181], v[56:59]
	v_mfma_f32_16x16x32_bf16 v[44:47], v[146:149], v[202:205], v[44:47]
	v_mfma_f32_16x16x32_bf16 v[40:43], v[154:157], v[202:205], v[40:43]
	v_mfma_f32_16x16x32_bf16 v[28:31], v[146:149], v[220:223], v[28:31]
	v_mfma_f32_16x16x32_bf16 v[24:27], v[154:157], v[220:223], v[24:27]
	v_mfma_f32_16x16x32_bf16 v[12:15], v[146:149], v[228:231], v[12:15]
	v_mfma_f32_16x16x32_bf16 v[8:11], v[154:157], v[228:231], v[8:11]
	s_setprio 0
	s_setprio 1
	v_mfma_f32_16x16x32_bf16 v[52:55], v[158:161], v[174:177], v[52:55]
	v_mfma_f32_16x16x32_bf16 v[48:51], v[166:169], v[174:177], v[48:51]
	v_mfma_f32_16x16x32_bf16 v[36:39], v[158:161], v[182:185], v[36:39]
	v_mfma_f32_16x16x32_bf16 v[32:35], v[166:169], v[182:185], v[32:35]
	v_mfma_f32_16x16x32_bf16 v[20:23], v[158:161], v[216:219], v[20:23]
	v_mfma_f32_16x16x32_bf16 v[16:19], v[166:169], v[216:219], v[16:19]
	v_mfma_f32_16x16x32_bf16 v[4:7], v[158:161], v[224:227], v[4:7]
	v_mfma_f32_16x16x32_bf16 v[0:3], v[166:169], v[224:227], v[0:3]
	v_mfma_f32_16x16x32_bf16 v[52:55], v[162:165], v[178:181], v[52:55]
	v_mfma_f32_16x16x32_bf16 v[48:51], v[170:173], v[178:181], v[48:51]
	v_mfma_f32_16x16x32_bf16 v[36:39], v[162:165], v[202:205], v[36:39]
	v_mfma_f32_16x16x32_bf16 v[32:35], v[170:173], v[202:205], v[32:35]
	v_mfma_f32_16x16x32_bf16 v[20:23], v[162:165], v[220:223], v[20:23]
	v_mfma_f32_16x16x32_bf16 v[16:19], v[170:173], v[220:223], v[16:19]
	v_mfma_f32_16x16x32_bf16 v[4:7], v[162:165], v[228:231], v[4:7]
	v_mfma_f32_16x16x32_bf16 v[0:3], v[170:173], v[228:231], v[0:3]
	s_setprio 0
	s_barrier
	s_add_u32 s66, s66, 0x100
	s_addc_u32 s67, s67, 0
	s_add_u32 s94, s94, 0x100
	s_addc_u32 s95, s95, 0
	s_cmp_ge_i32 vcc_lo, s48
	s_mov_b32 s82, vcc_lo
	s_cbranch_scc0 .LBB0_226
	s_mov_b64 s[88:89], 0x8000

.LBB0_247:
	s_add_i32 s61, s40, 2
	s_add_u32 s20, s38, 0xfffc0080
	s_addc_u32 s21, s39, -1
	s_add_i32 s52, 0, 0x10000
	s_cmp_eq_u32 s49, s40
	s_cselect_b32 s59, s35, s21
	s_cselect_b32 s58, s67, s20
	s_cselect_b32 s41, vcc_lo, s83
	s_cselect_b32 s40, vcc_hi, s82
	s_add_i32 s53, 0, 0x14000
	v_add_u32_e32 v148, s52, v168
	v_add_u32_e32 v164, s53, v168
	ds_read_b128 v[128:131], v148
	ds_read_b128 v[140:143], v148 offset:1024
	ds_read_b128 v[144:147], v148 offset:2048
	ds_read_b128 v[148:151], v148 offset:3072
	ds_read_b128 v[152:155], v164
	ds_read_b128 v[156:159], v164 offset:1024
	ds_read_b128 v[160:163], v164 offset:2048
	ds_read_b128 v[170:173], v164 offset:3072
	s_add_i32 m0, s46, 0xc000
	ds_read_b128 v[174:177], v169
	ds_read_b128 v[178:181], v169 offset:1024
	ds_read_b128 v[182:185], v169 offset:2048
	ds_read_b128 v[202:205], v169 offset:3072
	ds_read_b128 v[216:219], v169 offset:4096
	ds_read_b128 v[220:223], v169 offset:5120
	ds_read_b128 v[224:227], v169 offset:6144
	ds_read_b128 v[228:231], v169 offset:7168
	global_load_lds_dwordx4 v136, s[38:39]
	s_add_i32 m0, s46, 0xe000
	s_nop 0
	global_load_lds_dwordx4 v138, s[38:39]
	s_waitcnt vmcnt(8)
	s_waitcnt lgkmcnt(0)
	s_barrier
	s_setprio 1
	s_waitcnt lgkmcnt(0)
	v_mfma_f32_16x16x32_bf16 v[120:123], v[128:131], v[174:177], v[120:123]
	v_mfma_f32_16x16x32_bf16 v[124:127], v[144:147], v[174:177], v[124:127]
	v_mfma_f32_16x16x32_bf16 v[108:111], v[128:131], v[182:185], v[108:111]
	v_mfma_f32_16x16x32_bf16 v[104:107], v[144:147], v[182:185], v[104:107]
	v_mfma_f32_16x16x32_bf16 v[92:95], v[128:131], v[216:219], v[92:95]
	v_mfma_f32_16x16x32_bf16 v[88:91], v[144:147], v[216:219], v[88:91]
	v_mfma_f32_16x16x32_bf16 v[76:79], v[128:131], v[224:227], v[76:79]
	v_mfma_f32_16x16x32_bf16 v[72:75], v[144:147], v[224:227], v[72:75]
	v_mfma_f32_16x16x32_bf16 v[120:123], v[140:143], v[178:181], v[120:123]
	v_mfma_f32_16x16x32_bf16 v[124:127], v[148:151], v[178:181], v[124:127]
	v_mfma_f32_16x16x32_bf16 v[108:111], v[140:143], v[202:205], v[108:111]
	v_mfma_f32_16x16x32_bf16 v[104:107], v[148:151], v[202:205], v[104:107]
	v_mfma_f32_16x16x32_bf16 v[92:95], v[140:143], v[220:223], v[92:95]
	v_mfma_f32_16x16x32_bf16 v[88:91], v[148:151], v[220:223], v[88:91]
	v_mfma_f32_16x16x32_bf16 v[76:79], v[140:143], v[228:231], v[76:79]
	v_mfma_f32_16x16x32_bf16 v[72:75], v[148:151], v[228:231], v[72:75]
	s_setprio 0
	s_setprio 1
	v_mfma_f32_16x16x32_bf16 v[116:119], v[152:155], v[174:177], v[116:119]
	v_mfma_f32_16x16x32_bf16 v[112:115], v[160:163], v[174:177], v[112:115]
	v_mfma_f32_16x16x32_bf16 v[100:103], v[152:155], v[182:185], v[100:103]
	v_mfma_f32_16x16x32_bf16 v[96:99], v[160:163], v[182:185], v[96:99]
	v_mfma_f32_16x16x32_bf16 v[84:87], v[152:155], v[216:219], v[84:87]
	v_mfma_f32_16x16x32_bf16 v[80:83], v[160:163], v[216:219], v[80:83]
	v_mfma_f32_16x16x32_bf16 v[68:71], v[152:155], v[224:227], v[68:71]
	v_mfma_f32_16x16x32_bf16 v[64:67], v[160:163], v[224:227], v[64:67]
	v_mfma_f32_16x16x32_bf16 v[116:119], v[156:159], v[178:181], v[116:119]
	v_mfma_f32_16x16x32_bf16 v[112:115], v[170:173], v[178:181], v[112:115]
	v_mfma_f32_16x16x32_bf16 v[100:103], v[156:159], v[202:205], v[100:103]
	v_mfma_f32_16x16x32_bf16 v[96:99], v[170:173], v[202:205], v[96:99]
	v_mfma_f32_16x16x32_bf16 v[84:87], v[156:159], v[220:223], v[84:87]
	v_mfma_f32_16x16x32_bf16 v[80:83], v[170:173], v[220:223], v[80:83]
	v_mfma_f32_16x16x32_bf16 v[68:71], v[156:159], v[228:231], v[68:71]
	v_mfma_f32_16x16x32_bf16 v[64:67], v[170:173], v[228:231], v[64:67]
	s_setprio 0
	s_barrier
	s_add_i32 s20, s52, s55
	v_lshl_add_u64 v[164:165], s[40:41], 0, v[134:135]
	s_mov_b32 m0, s20
	ds_read_b128 v[174:177], v169 offset:16384
	ds_read_b128 v[178:181], v169 offset:17408
	ds_read_b128 v[182:185], v169 offset:18432
	ds_read_b128 v[202:205], v169 offset:19456
	ds_read_b128 v[216:219], v169 offset:20480
	ds_read_b128 v[220:223], v169 offset:21504
	ds_read_b128 v[224:227], v169 offset:22528
	ds_read_b128 v[228:231], v169 offset:23552
	global_load_lds_dwordx4 v[164:165], off
	s_add_i32 m0, s20, 0x2000
	s_add_u32 s20, s40, 0x40000
	v_lshl_add_u64 v[186:187], s[40:41], 0, v[132:133]
	s_addc_u32 s21, s41, 0
	s_add_i32 s52, s53, s55
	global_load_lds_dwordx4 v[186:187], off
	s_mov_b32 m0, s52
	v_lshl_add_u64 v[196:197], s[58:59], 0, v[132:133]
	global_load_lds_dwordx4 v134, s[20:21]
	s_add_i32 m0, s52, 0x2000
	s_nop 0
	global_load_lds_dwordx4 v132, s[20:21]
	v_lshl_add_u64 v[194:195], s[58:59], 0, v[134:135]
	s_mov_b32 m0, s46
	s_nop 0
	global_load_lds_dwordx4 v[194:195], off
	s_mov_b32 m0, s47
	s_nop 0
	global_load_lds_dwordx4 v[196:197], off
	s_waitcnt vmcnt(8)
	s_waitcnt lgkmcnt(0)
	s_barrier
	s_setprio 1
	s_waitcnt lgkmcnt(0)
	v_mfma_f32_16x16x32_bf16 v[60:63], v[128:131], v[174:177], v[60:63]
	v_mfma_f32_16x16x32_bf16 v[56:59], v[144:147], v[174:177], v[56:59]
	v_mfma_f32_16x16x32_bf16 v[44:47], v[128:131], v[182:185], v[44:47]
	v_mfma_f32_16x16x32_bf16 v[40:43], v[144:147], v[182:185], v[40:43]
	v_mfma_f32_16x16x32_bf16 v[28:31], v[128:131], v[216:219], v[28:31]
	v_mfma_f32_16x16x32_bf16 v[24:27], v[144:147], v[216:219], v[24:27]
	v_mfma_f32_16x16x32_bf16 v[12:15], v[128:131], v[224:227], v[12:15]
	v_mfma_f32_16x16x32_bf16 v[8:11], v[144:147], v[224:227], v[8:11]
	v_mfma_f32_16x16x32_bf16 v[60:63], v[140:143], v[178:181], v[60:63]
	v_mfma_f32_16x16x32_bf16 v[56:59], v[148:151], v[178:181], v[56:59]
	v_mfma_f32_16x16x32_bf16 v[44:47], v[140:143], v[202:205], v[44:47]
	v_mfma_f32_16x16x32_bf16 v[40:43], v[148:151], v[202:205], v[40:43]
	v_mfma_f32_16x16x32_bf16 v[28:31], v[140:143], v[220:223], v[28:31]
	v_mfma_f32_16x16x32_bf16 v[24:27], v[148:151], v[220:223], v[24:27]
	v_mfma_f32_16x16x32_bf16 v[12:15], v[140:143], v[228:231], v[12:15]
	v_mfma_f32_16x16x32_bf16 v[8:11], v[148:151], v[228:231], v[8:11]
	s_setprio 0
	s_setprio 1
	v_mfma_f32_16x16x32_bf16 v[52:55], v[152:155], v[174:177], v[52:55]
	v_mfma_f32_16x16x32_bf16 v[48:51], v[160:163], v[174:177], v[48:51]
	v_mfma_f32_16x16x32_bf16 v[36:39], v[152:155], v[182:185], v[36:39]
	v_mfma_f32_16x16x32_bf16 v[32:35], v[160:163], v[182:185], v[32:35]
	v_mfma_f32_16x16x32_bf16 v[20:23], v[152:155], v[216:219], v[20:23]
	v_mfma_f32_16x16x32_bf16 v[16:19], v[160:163], v[216:219], v[16:19]
	v_mfma_f32_16x16x32_bf16 v[4:7], v[152:155], v[224:227], v[4:7]
	v_mfma_f32_16x16x32_bf16 v[0:3], v[160:163], v[224:227], v[0:3]
	v_mfma_f32_16x16x32_bf16 v[52:55], v[156:159], v[178:181], v[52:55]
	v_mfma_f32_16x16x32_bf16 v[48:51], v[170:173], v[178:181], v[48:51]
	v_mfma_f32_16x16x32_bf16 v[36:39], v[156:159], v[202:205], v[36:39]
	v_mfma_f32_16x16x32_bf16 v[32:35], v[170:173], v[202:205], v[32:35]
	v_mfma_f32_16x16x32_bf16 v[20:23], v[156:159], v[220:223], v[20:23]
	v_mfma_f32_16x16x32_bf16 v[16:19], v[170:173], v[220:223], v[16:19]
	v_mfma_f32_16x16x32_bf16 v[4:7], v[156:159], v[228:231], v[4:7]
	v_mfma_f32_16x16x32_bf16 v[0:3], v[170:173], v[228:231], v[0:3]
	s_setprio 0
	s_barrier
	s_add_i32 s52, 0, 0x18000
	s_add_i32 s53, 0, 0x1c000
	v_add_u32_e32 v148, s52, v168
	v_add_u32_e32 v170, s53, v168
	ds_read_b128 v[128:131], v148
	ds_read_b128 v[140:143], v148 offset:1024
	ds_read_b128 v[144:147], v148 offset:2048
	ds_read_b128 v[148:151], v148 offset:3072
	ds_read_b128 v[152:155], v170
	ds_read_b128 v[156:159], v170 offset:1024
	ds_read_b128 v[160:163], v170 offset:2048
	ds_read_b128 v[170:173], v170 offset:3072
	s_add_u32 s20, s58, 0x40000
	s_addc_u32 s21, s59, 0
	s_mov_b32 m0, s25
	ds_read_b128 v[174:177], v169 offset:32768
	ds_read_b128 v[178:181], v169 offset:33792
	ds_read_b128 v[182:185], v169 offset:34816
	ds_read_b128 v[202:205], v169 offset:35840
	ds_read_b128 v[216:219], v169 offset:36864
	ds_read_b128 v[220:223], v169 offset:37888
	ds_read_b128 v[224:227], v169 offset:38912
	ds_read_b128 v[228:231], v169 offset:39936
	global_load_lds_dwordx4 v134, s[20:21]
	s_mov_b32 m0, s44
	s_nop 0
	global_load_lds_dwordx4 v132, s[20:21]
	s_waitcnt vmcnt(8)
	s_waitcnt lgkmcnt(0)
	s_barrier
	s_setprio 1
	s_waitcnt lgkmcnt(0)
	v_mfma_f32_16x16x32_bf16 v[120:123], v[128:131], v[174:177], v[120:123]
	v_mfma_f32_16x16x32_bf16 v[124:127], v[144:147], v[174:177], v[124:127]
	v_mfma_f32_16x16x32_bf16 v[108:111], v[128:131], v[182:185], v[108:111]
	v_mfma_f32_16x16x32_bf16 v[104:107], v[144:147], v[182:185], v[104:107]
	v_mfma_f32_16x16x32_bf16 v[92:95], v[128:131], v[216:219], v[92:95]
	v_mfma_f32_16x16x32_bf16 v[88:91], v[144:147], v[216:219], v[88:91]
	v_mfma_f32_16x16x32_bf16 v[76:79], v[128:131], v[224:227], v[76:79]
	v_mfma_f32_16x16x32_bf16 v[72:75], v[144:147], v[224:227], v[72:75]
	v_mfma_f32_16x16x32_bf16 v[120:123], v[140:143], v[178:181], v[120:123]
	v_mfma_f32_16x16x32_bf16 v[124:127], v[148:151], v[178:181], v[124:127]
	v_mfma_f32_16x16x32_bf16 v[108:111], v[140:143], v[202:205], v[108:111]
	v_mfma_f32_16x16x32_bf16 v[104:107], v[148:151], v[202:205], v[104:107]
	v_mfma_f32_16x16x32_bf16 v[92:95], v[140:143], v[220:223], v[92:95]
	v_mfma_f32_16x16x32_bf16 v[88:91], v[148:151], v[220:223], v[88:91]
	v_mfma_f32_16x16x32_bf16 v[76:79], v[140:143], v[228:231], v[76:79]
	v_mfma_f32_16x16x32_bf16 v[72:75], v[148:151], v[228:231], v[72:75]
	s_setprio 0
	s_setprio 1
	v_mfma_f32_16x16x32_bf16 v[116:119], v[152:155], v[174:177], v[116:119]
	v_mfma_f32_16x16x32_bf16 v[112:115], v[160:163], v[174:177], v[112:115]
	v_mfma_f32_16x16x32_bf16 v[100:103], v[152:155], v[182:185], v[100:103]
	v_mfma_f32_16x16x32_bf16 v[96:99], v[160:163], v[182:185], v[96:99]
	v_mfma_f32_16x16x32_bf16 v[84:87], v[152:155], v[216:219], v[84:87]
	v_mfma_f32_16x16x32_bf16 v[80:83], v[160:163], v[216:219], v[80:83]
	v_mfma_f32_16x16x32_bf16 v[68:71], v[152:155], v[224:227], v[68:71]
	v_mfma_f32_16x16x32_bf16 v[64:67], v[160:163], v[224:227], v[64:67]
	v_mfma_f32_16x16x32_bf16 v[116:119], v[156:159], v[178:181], v[116:119]
	v_mfma_f32_16x16x32_bf16 v[112:115], v[170:173], v[178:181], v[112:115]
	v_mfma_f32_16x16x32_bf16 v[100:103], v[156:159], v[202:205], v[100:103]
	v_mfma_f32_16x16x32_bf16 v[96:99], v[170:173], v[202:205], v[96:99]
	v_mfma_f32_16x16x32_bf16 v[84:87], v[156:159], v[220:223], v[84:87]
	v_mfma_f32_16x16x32_bf16 v[80:83], v[170:173], v[220:223], v[80:83]
	v_mfma_f32_16x16x32_bf16 v[68:71], v[156:159], v[228:231], v[68:71]
	v_mfma_f32_16x16x32_bf16 v[64:67], v[170:173], v[228:231], v[64:67]
	s_setprio 0
	s_barrier
	s_add_i32 s20, s52, s55
	v_lshl_add_u64 v[164:165], v[164:165], 0, s[62:63]
	s_mov_b32 m0, s20
	ds_read_b128 v[174:177], v169 offset:49152
	ds_read_b128 v[178:181], v169 offset:50176
	ds_read_b128 v[182:185], v169 offset:51200
	ds_read_b128 v[202:205], v169 offset:52224
	ds_read_b128 v[216:219], v169 offset:53248
	ds_read_b128 v[220:223], v169 offset:54272
	ds_read_b128 v[224:227], v169 offset:55296
	ds_read_b128 v[228:231], v169 offset:56320
	global_load_lds_dwordx4 v[164:165], off
	s_add_i32 m0, s20, 0x2000
	s_add_u32 s20, s40, 0x40080
	v_lshl_add_u64 v[164:165], v[186:187], 0, s[62:63]
	s_addc_u32 s21, s41, 0
	s_add_i32 s40, s53, s55
	global_load_lds_dwordx4 v[164:165], off
	s_mov_b32 m0, s40
	s_nop 0
	global_load_lds_dwordx4 v134, s[20:21]
	s_add_i32 m0, s40, 0x2000
	s_nop 0
	global_load_lds_dwordx4 v132, s[20:21]
	v_lshl_add_u64 v[164:165], v[194:195], 0, s[62:63]
	s_mov_b32 m0, s56
	s_nop 0
	global_load_lds_dwordx4 v[164:165], off
	v_lshl_add_u64 v[164:165], v[196:197], 0, s[62:63]
	s_mov_b32 m0, s57
	s_nop 0
	global_load_lds_dwordx4 v[164:165], off
	s_waitcnt vmcnt(8)
	s_waitcnt lgkmcnt(0)
	s_barrier
	s_setprio 1
	s_waitcnt lgkmcnt(0)
	v_mfma_f32_16x16x32_bf16 v[60:63], v[128:131], v[174:177], v[60:63]
	v_mfma_f32_16x16x32_bf16 v[56:59], v[144:147], v[174:177], v[56:59]
	v_mfma_f32_16x16x32_bf16 v[44:47], v[128:131], v[182:185], v[44:47]
	v_mfma_f32_16x16x32_bf16 v[40:43], v[144:147], v[182:185], v[40:43]
	v_mfma_f32_16x16x32_bf16 v[28:31], v[128:131], v[216:219], v[28:31]
	v_mfma_f32_16x16x32_bf16 v[24:27], v[144:147], v[216:219], v[24:27]
	v_mfma_f32_16x16x32_bf16 v[12:15], v[128:131], v[224:227], v[12:15]
	v_mfma_f32_16x16x32_bf16 v[8:11], v[144:147], v[224:227], v[8:11]
	v_mfma_f32_16x16x32_bf16 v[60:63], v[140:143], v[178:181], v[60:63]
	v_mfma_f32_16x16x32_bf16 v[56:59], v[148:151], v[178:181], v[56:59]
	v_mfma_f32_16x16x32_bf16 v[44:47], v[140:143], v[202:205], v[44:47]
	v_mfma_f32_16x16x32_bf16 v[40:43], v[148:151], v[202:205], v[40:43]
	v_mfma_f32_16x16x32_bf16 v[28:31], v[140:143], v[220:223], v[28:31]
	v_mfma_f32_16x16x32_bf16 v[24:27], v[148:151], v[220:223], v[24:27]
	v_mfma_f32_16x16x32_bf16 v[12:15], v[140:143], v[228:231], v[12:15]
	v_mfma_f32_16x16x32_bf16 v[8:11], v[148:151], v[228:231], v[8:11]
	s_setprio 0
	s_setprio 1
	v_mfma_f32_16x16x32_bf16 v[52:55], v[152:155], v[174:177], v[52:55]
	v_mfma_f32_16x16x32_bf16 v[48:51], v[160:163], v[174:177], v[48:51]
	v_mfma_f32_16x16x32_bf16 v[36:39], v[152:155], v[182:185], v[36:39]
	v_mfma_f32_16x16x32_bf16 v[32:35], v[160:163], v[182:185], v[32:35]
	v_mfma_f32_16x16x32_bf16 v[20:23], v[152:155], v[216:219], v[20:23]
	v_mfma_f32_16x16x32_bf16 v[16:19], v[160:163], v[216:219], v[16:19]
	v_mfma_f32_16x16x32_bf16 v[4:7], v[152:155], v[224:227], v[4:7]
	v_mfma_f32_16x16x32_bf16 v[0:3], v[160:163], v[224:227], v[0:3]
	v_mfma_f32_16x16x32_bf16 v[52:55], v[156:159], v[178:181], v[52:55]
	v_mfma_f32_16x16x32_bf16 v[48:51], v[170:173], v[178:181], v[48:51]
	v_mfma_f32_16x16x32_bf16 v[36:39], v[156:159], v[202:205], v[36:39]
	v_mfma_f32_16x16x32_bf16 v[32:35], v[170:173], v[202:205], v[32:35]
	v_mfma_f32_16x16x32_bf16 v[20:23], v[156:159], v[220:223], v[20:23]
	v_mfma_f32_16x16x32_bf16 v[16:19], v[170:173], v[220:223], v[16:19]
	v_mfma_f32_16x16x32_bf16 v[4:7], v[156:159], v[228:231], v[4:7]
	v_mfma_f32_16x16x32_bf16 v[0:3], v[170:173], v[228:231], v[0:3]
	s_setprio 0
	s_barrier
	s_add_u32 s38, s38, 0x100
	s_addc_u32 s39, s39, 0
	s_add_u32 s82, s82, 0x100
	s_addc_u32 s83, s83, 0
	s_cmp_ge_i32 s61, s80
	s_mov_b32 s40, s61
	s_cbranch_scc0 .LBB0_247

.LBB0_294:
	s_add_i32 vcc_lo, s82, 2
	s_add_u32 s20, s66, 0xfffc0080
	s_addc_u32 s21, s67, -1
	s_add_i32 vcc_hi, 0, 0x10000
	s_cmp_eq_u32 s60, s82
	s_cselect_b32 s87, s39, s21
	s_cselect_b32 s86, s41, s20
	v_add_u32_e32 v148, vcc_hi, v151
	s_cselect_b32 s83, s88, s95
	s_cselect_b32 s82, s89, s94
	s_add_i32 s52, 0, 0x14000
	ds_read_b128 v[140:143], v148
	ds_read_b128 v[144:147], v148 offset:1024
	ds_read_b128 v[154:157], v148 offset:2048
	ds_read_b128 v[158:161], v148 offset:3072
	v_add_u32_e32 v148, s52, v151
	ds_read_b128 v[162:165], v148
	ds_read_b128 v[166:169], v148 offset:1024
	ds_read_b128 v[170:173], v148 offset:2048
	ds_read_b128 v[174:177], v148 offset:3072
	s_add_i32 m0, s13, 0xc000
	ds_read_b128 v[178:181], v152
	ds_read_b128 v[182:185], v152 offset:1024
	ds_read_b128 v[202:205], v152 offset:2048
	ds_read_b128 v[216:219], v152 offset:3072
	ds_read_b128 v[220:223], v152 offset:4096
	ds_read_b128 v[224:227], v152 offset:5120
	ds_read_b128 v[228:231], v152 offset:6144
	ds_read_b128 v[232:235], v152 offset:7168
	global_load_lds_dwordx4 v136, s[66:67]
	s_add_i32 m0, s13, 0xe000
	s_nop 0
	global_load_lds_dwordx4 v138, s[66:67]
	s_waitcnt vmcnt(8)
	s_waitcnt lgkmcnt(0)
	s_barrier
	s_setprio 1
	s_waitcnt lgkmcnt(0)
	v_mfma_f32_16x16x32_bf16 v[120:123], v[140:143], v[178:181], v[120:123]
	v_mfma_f32_16x16x32_bf16 v[124:127], v[154:157], v[178:181], v[124:127]
	v_mfma_f32_16x16x32_bf16 v[108:111], v[140:143], v[202:205], v[108:111]
	v_mfma_f32_16x16x32_bf16 v[104:107], v[154:157], v[202:205], v[104:107]
	v_mfma_f32_16x16x32_bf16 v[92:95], v[140:143], v[220:223], v[92:95]
	v_mfma_f32_16x16x32_bf16 v[88:91], v[154:157], v[220:223], v[88:91]
	v_mfma_f32_16x16x32_bf16 v[76:79], v[140:143], v[228:231], v[76:79]
	v_mfma_f32_16x16x32_bf16 v[72:75], v[154:157], v[228:231], v[72:75]
	v_mfma_f32_16x16x32_bf16 v[120:123], v[144:147], v[182:185], v[120:123]
	v_mfma_f32_16x16x32_bf16 v[124:127], v[158:161], v[182:185], v[124:127]
	v_mfma_f32_16x16x32_bf16 v[108:111], v[144:147], v[216:219], v[108:111]
	v_mfma_f32_16x16x32_bf16 v[104:107], v[158:161], v[216:219], v[104:107]
	v_mfma_f32_16x16x32_bf16 v[92:95], v[144:147], v[224:227], v[92:95]
	v_mfma_f32_16x16x32_bf16 v[88:91], v[158:161], v[224:227], v[88:91]
	v_mfma_f32_16x16x32_bf16 v[76:79], v[144:147], v[232:235], v[76:79]
	v_mfma_f32_16x16x32_bf16 v[72:75], v[158:161], v[232:235], v[72:75]
	s_setprio 0
	s_setprio 1
	v_mfma_f32_16x16x32_bf16 v[116:119], v[162:165], v[178:181], v[116:119]
	v_mfma_f32_16x16x32_bf16 v[112:115], v[170:173], v[178:181], v[112:115]
	v_mfma_f32_16x16x32_bf16 v[100:103], v[162:165], v[202:205], v[100:103]
	v_mfma_f32_16x16x32_bf16 v[96:99], v[170:173], v[202:205], v[96:99]
	v_mfma_f32_16x16x32_bf16 v[84:87], v[162:165], v[220:223], v[84:87]
	v_mfma_f32_16x16x32_bf16 v[80:83], v[170:173], v[220:223], v[80:83]
	v_mfma_f32_16x16x32_bf16 v[68:71], v[162:165], v[228:231], v[68:71]
	v_mfma_f32_16x16x32_bf16 v[64:67], v[170:173], v[228:231], v[64:67]
	v_mfma_f32_16x16x32_bf16 v[116:119], v[166:169], v[182:185], v[116:119]
	v_mfma_f32_16x16x32_bf16 v[112:115], v[174:177], v[182:185], v[112:115]
	v_mfma_f32_16x16x32_bf16 v[100:103], v[166:169], v[216:219], v[100:103]
	v_mfma_f32_16x16x32_bf16 v[96:99], v[174:177], v[216:219], v[96:99]
	v_mfma_f32_16x16x32_bf16 v[84:87], v[166:169], v[224:227], v[84:87]
	v_mfma_f32_16x16x32_bf16 v[80:83], v[174:177], v[224:227], v[80:83]
	v_mfma_f32_16x16x32_bf16 v[68:71], v[166:169], v[232:235], v[68:71]
	v_mfma_f32_16x16x32_bf16 v[64:67], v[174:177], v[232:235], v[64:67]
	s_setprio 0
	s_barrier
	s_add_i32 s20, vcc_hi, s12
	v_lshl_add_u64 v[186:187], s[82:83], 0, v[132:133]
	s_mov_b32 m0, s20
	ds_read_b128 v[178:181], v152 offset:16384
	ds_read_b128 v[182:185], v152 offset:17408
	ds_read_b128 v[202:205], v152 offset:18432
	ds_read_b128 v[216:219], v152 offset:19456
	ds_read_b128 v[220:223], v152 offset:20480
	ds_read_b128 v[224:227], v152 offset:21504
	ds_read_b128 v[228:231], v152 offset:22528
	ds_read_b128 v[232:235], v152 offset:23552
	global_load_lds_dwordx4 v[186:187], off
	s_add_i32 m0, s20, 0x2000
	s_add_u32 s20, s82, 0x40000
	v_lshl_add_u64 v[194:195], s[82:83], 0, v[128:129]
	s_addc_u32 s21, s83, 0
	s_add_i32 s52, s52, s12
	global_load_lds_dwordx4 v[194:195], off
	s_mov_b32 m0, s52
	v_lshl_add_u64 v[236:237], s[86:87], 0, v[130:131]
	global_load_lds_dwordx4 v132, s[20:21]
	s_add_i32 m0, s52, 0x2000
	s_nop 0
	global_load_lds_dwordx4 v128, s[20:21]
	v_lshl_add_u64 v[196:197], s[86:87], 0, v[134:135]
	s_mov_b32 m0, s13
	s_nop 0
	global_load_lds_dwordx4 v[196:197], off
	s_mov_b32 m0, s28
	s_nop 0
	global_load_lds_dwordx4 v[236:237], off
	s_waitcnt vmcnt(8)
	s_waitcnt lgkmcnt(0)
	s_barrier
	s_setprio 1
	s_waitcnt lgkmcnt(0)
	v_mfma_f32_16x16x32_bf16 v[60:63], v[140:143], v[178:181], v[60:63]
	v_mfma_f32_16x16x32_bf16 v[56:59], v[154:157], v[178:181], v[56:59]
	v_mfma_f32_16x16x32_bf16 v[44:47], v[140:143], v[202:205], v[44:47]
	v_mfma_f32_16x16x32_bf16 v[40:43], v[154:157], v[202:205], v[40:43]
	v_mfma_f32_16x16x32_bf16 v[28:31], v[140:143], v[220:223], v[28:31]
	v_mfma_f32_16x16x32_bf16 v[24:27], v[154:157], v[220:223], v[24:27]
	v_mfma_f32_16x16x32_bf16 v[12:15], v[140:143], v[228:231], v[12:15]
	v_mfma_f32_16x16x32_bf16 v[8:11], v[154:157], v[228:231], v[8:11]
	v_mfma_f32_16x16x32_bf16 v[60:63], v[144:147], v[182:185], v[60:63]
	v_mfma_f32_16x16x32_bf16 v[56:59], v[158:161], v[182:185], v[56:59]
	v_mfma_f32_16x16x32_bf16 v[44:47], v[144:147], v[216:219], v[44:47]
	v_mfma_f32_16x16x32_bf16 v[40:43], v[158:161], v[216:219], v[40:43]
	v_mfma_f32_16x16x32_bf16 v[28:31], v[144:147], v[224:227], v[28:31]
	v_mfma_f32_16x16x32_bf16 v[24:27], v[158:161], v[224:227], v[24:27]
	v_mfma_f32_16x16x32_bf16 v[12:15], v[144:147], v[232:235], v[12:15]
	v_mfma_f32_16x16x32_bf16 v[8:11], v[158:161], v[232:235], v[8:11]
	s_setprio 0
	s_setprio 1
	v_mfma_f32_16x16x32_bf16 v[52:55], v[162:165], v[178:181], v[52:55]
	v_mfma_f32_16x16x32_bf16 v[48:51], v[170:173], v[178:181], v[48:51]
	v_mfma_f32_16x16x32_bf16 v[36:39], v[162:165], v[202:205], v[36:39]
	v_mfma_f32_16x16x32_bf16 v[32:35], v[170:173], v[202:205], v[32:35]
	v_mfma_f32_16x16x32_bf16 v[20:23], v[162:165], v[220:223], v[20:23]
	v_mfma_f32_16x16x32_bf16 v[16:19], v[170:173], v[220:223], v[16:19]
	v_mfma_f32_16x16x32_bf16 v[4:7], v[162:165], v[228:231], v[4:7]
	v_mfma_f32_16x16x32_bf16 v[0:3], v[170:173], v[228:231], v[0:3]
	v_mfma_f32_16x16x32_bf16 v[52:55], v[166:169], v[182:185], v[52:55]
	v_mfma_f32_16x16x32_bf16 v[48:51], v[174:177], v[182:185], v[48:51]
	v_mfma_f32_16x16x32_bf16 v[36:39], v[166:169], v[216:219], v[36:39]
	v_mfma_f32_16x16x32_bf16 v[32:35], v[174:177], v[216:219], v[32:35]
	v_mfma_f32_16x16x32_bf16 v[20:23], v[166:169], v[224:227], v[20:23]
	v_mfma_f32_16x16x32_bf16 v[16:19], v[174:177], v[224:227], v[16:19]
	v_mfma_f32_16x16x32_bf16 v[4:7], v[166:169], v[232:235], v[4:7]
	v_mfma_f32_16x16x32_bf16 v[0:3], v[174:177], v[232:235], v[0:3]
	s_setprio 0
	s_barrier
	s_add_i32 s52, 0, 0x18000
	v_add_u32_e32 v148, s52, v151
	s_add_i32 s53, 0, 0x1c000
	ds_read_b128 v[140:143], v148
	ds_read_b128 v[144:147], v148 offset:1024
	ds_read_b128 v[154:157], v148 offset:2048
	ds_read_b128 v[158:161], v148 offset:3072
	v_add_u32_e32 v148, s53, v151
	ds_read_b128 v[162:165], v148
	ds_read_b128 v[166:169], v148 offset:1024
	ds_read_b128 v[170:173], v148 offset:2048
	ds_read_b128 v[174:177], v148 offset:3072
	s_add_u32 s20, s86, 0x40000
	s_addc_u32 s21, s87, 0
	s_mov_b32 m0, s46
	ds_read_b128 v[178:181], v152 offset:32768
	ds_read_b128 v[182:185], v152 offset:33792
	ds_read_b128 v[202:205], v152 offset:34816
	ds_read_b128 v[216:219], v152 offset:35840
	ds_read_b128 v[220:223], v152 offset:36864
	ds_read_b128 v[224:227], v152 offset:37888
	ds_read_b128 v[228:231], v152 offset:38912
	ds_read_b128 v[232:235], v152 offset:39936
	global_load_lds_dwordx4 v134, s[20:21]
	s_mov_b32 m0, s47
	s_nop 0
	global_load_lds_dwordx4 v130, s[20:21]
	s_waitcnt vmcnt(8)
	s_waitcnt lgkmcnt(0)
	s_barrier
	s_setprio 1
	s_waitcnt lgkmcnt(0)
	v_mfma_f32_16x16x32_bf16 v[120:123], v[140:143], v[178:181], v[120:123]
	v_mfma_f32_16x16x32_bf16 v[124:127], v[154:157], v[178:181], v[124:127]
	v_mfma_f32_16x16x32_bf16 v[108:111], v[140:143], v[202:205], v[108:111]
	v_mfma_f32_16x16x32_bf16 v[104:107], v[154:157], v[202:205], v[104:107]
	v_mfma_f32_16x16x32_bf16 v[92:95], v[140:143], v[220:223], v[92:95]
	v_mfma_f32_16x16x32_bf16 v[88:91], v[154:157], v[220:223], v[88:91]
	v_mfma_f32_16x16x32_bf16 v[76:79], v[140:143], v[228:231], v[76:79]
	v_mfma_f32_16x16x32_bf16 v[72:75], v[154:157], v[228:231], v[72:75]
	v_mfma_f32_16x16x32_bf16 v[120:123], v[144:147], v[182:185], v[120:123]
	v_mfma_f32_16x16x32_bf16 v[124:127], v[158:161], v[182:185], v[124:127]
	v_mfma_f32_16x16x32_bf16 v[108:111], v[144:147], v[216:219], v[108:111]
	v_mfma_f32_16x16x32_bf16 v[104:107], v[158:161], v[216:219], v[104:107]
	v_mfma_f32_16x16x32_bf16 v[92:95], v[144:147], v[224:227], v[92:95]
	v_mfma_f32_16x16x32_bf16 v[88:91], v[158:161], v[224:227], v[88:91]
	v_mfma_f32_16x16x32_bf16 v[76:79], v[144:147], v[232:235], v[76:79]
	v_mfma_f32_16x16x32_bf16 v[72:75], v[158:161], v[232:235], v[72:75]
	s_setprio 0
	s_setprio 1
	v_mfma_f32_16x16x32_bf16 v[116:119], v[162:165], v[178:181], v[116:119]
	v_mfma_f32_16x16x32_bf16 v[112:115], v[170:173], v[178:181], v[112:115]
	v_mfma_f32_16x16x32_bf16 v[100:103], v[162:165], v[202:205], v[100:103]
	v_mfma_f32_16x16x32_bf16 v[96:99], v[170:173], v[202:205], v[96:99]
	v_mfma_f32_16x16x32_bf16 v[84:87], v[162:165], v[220:223], v[84:87]
	v_mfma_f32_16x16x32_bf16 v[80:83], v[170:173], v[220:223], v[80:83]
	v_mfma_f32_16x16x32_bf16 v[68:71], v[162:165], v[228:231], v[68:71]
	v_mfma_f32_16x16x32_bf16 v[64:67], v[170:173], v[228:231], v[64:67]
	v_mfma_f32_16x16x32_bf16 v[116:119], v[166:169], v[182:185], v[116:119]
	v_mfma_f32_16x16x32_bf16 v[112:115], v[174:177], v[182:185], v[112:115]
	v_mfma_f32_16x16x32_bf16 v[100:103], v[166:169], v[216:219], v[100:103]
	v_mfma_f32_16x16x32_bf16 v[96:99], v[174:177], v[216:219], v[96:99]
	v_mfma_f32_16x16x32_bf16 v[84:87], v[166:169], v[224:227], v[84:87]
	v_mfma_f32_16x16x32_bf16 v[80:83], v[174:177], v[224:227], v[80:83]
	v_mfma_f32_16x16x32_bf16 v[68:71], v[166:169], v[232:235], v[68:71]
	v_mfma_f32_16x16x32_bf16 v[64:67], v[174:177], v[232:235], v[64:67]
	s_setprio 0
	s_barrier
	s_add_i32 s20, s52, s12
	v_lshl_add_u64 v[186:187], v[186:187], 0, s[62:63]
	s_mov_b32 m0, s20
	ds_read_b128 v[178:181], v152 offset:49152
	ds_read_b128 v[182:185], v152 offset:50176
	ds_read_b128 v[202:205], v152 offset:51200
	ds_read_b128 v[216:219], v152 offset:52224
	ds_read_b128 v[220:223], v152 offset:53248
	ds_read_b128 v[224:227], v152 offset:54272
	ds_read_b128 v[228:231], v152 offset:55296
	ds_read_b128 v[232:235], v152 offset:56320
	global_load_lds_dwordx4 v[186:187], off
	s_add_i32 m0, s20, 0x2000
	s_add_u32 s20, s82, 0x40080
	v_lshl_add_u64 v[186:187], v[194:195], 0, s[62:63]
	s_addc_u32 s21, s83, 0
	s_add_i32 s52, s53, s12
	global_load_lds_dwordx4 v[186:187], off
	s_mov_b32 m0, s52
	s_nop 0
	global_load_lds_dwordx4 v132, s[20:21]
	s_add_i32 m0, s52, 0x2000
	s_nop 0
	global_load_lds_dwordx4 v128, s[20:21]
	v_lshl_add_u64 v[186:187], v[196:197], 0, s[62:63]
	s_mov_b32 m0, s48
	s_nop 0
	global_load_lds_dwordx4 v[186:187], off
	v_lshl_add_u64 v[186:187], v[236:237], 0, s[62:63]
	s_mov_b32 m0, s49
	s_nop 0
	global_load_lds_dwordx4 v[186:187], off
	s_waitcnt vmcnt(8)
	s_waitcnt lgkmcnt(0)
	s_barrier
	s_setprio 1
	s_waitcnt lgkmcnt(0)
	v_mfma_f32_16x16x32_bf16 v[60:63], v[140:143], v[178:181], v[60:63]
	v_mfma_f32_16x16x32_bf16 v[56:59], v[154:157], v[178:181], v[56:59]
	v_mfma_f32_16x16x32_bf16 v[44:47], v[140:143], v[202:205], v[44:47]
	v_mfma_f32_16x16x32_bf16 v[40:43], v[154:157], v[202:205], v[40:43]
	v_mfma_f32_16x16x32_bf16 v[28:31], v[140:143], v[220:223], v[28:31]
	v_mfma_f32_16x16x32_bf16 v[24:27], v[154:157], v[220:223], v[24:27]
	v_mfma_f32_16x16x32_bf16 v[12:15], v[140:143], v[228:231], v[12:15]
	v_mfma_f32_16x16x32_bf16 v[8:11], v[154:157], v[228:231], v[8:11]
	v_mfma_f32_16x16x32_bf16 v[60:63], v[144:147], v[182:185], v[60:63]
	v_mfma_f32_16x16x32_bf16 v[56:59], v[158:161], v[182:185], v[56:59]
	v_mfma_f32_16x16x32_bf16 v[44:47], v[144:147], v[216:219], v[44:47]
	v_mfma_f32_16x16x32_bf16 v[40:43], v[158:161], v[216:219], v[40:43]
	v_mfma_f32_16x16x32_bf16 v[28:31], v[144:147], v[224:227], v[28:31]
	v_mfma_f32_16x16x32_bf16 v[24:27], v[158:161], v[224:227], v[24:27]
	v_mfma_f32_16x16x32_bf16 v[12:15], v[144:147], v[232:235], v[12:15]
	v_mfma_f32_16x16x32_bf16 v[8:11], v[158:161], v[232:235], v[8:11]
	s_setprio 0
	s_setprio 1
	v_mfma_f32_16x16x32_bf16 v[52:55], v[162:165], v[178:181], v[52:55]
	v_mfma_f32_16x16x32_bf16 v[48:51], v[170:173], v[178:181], v[48:51]
	v_mfma_f32_16x16x32_bf16 v[36:39], v[162:165], v[202:205], v[36:39]
	v_mfma_f32_16x16x32_bf16 v[32:35], v[170:173], v[202:205], v[32:35]
	v_mfma_f32_16x16x32_bf16 v[20:23], v[162:165], v[220:223], v[20:23]
	v_mfma_f32_16x16x32_bf16 v[16:19], v[170:173], v[220:223], v[16:19]
	v_mfma_f32_16x16x32_bf16 v[4:7], v[162:165], v[228:231], v[4:7]
	v_mfma_f32_16x16x32_bf16 v[0:3], v[170:173], v[228:231], v[0:3]
	v_mfma_f32_16x16x32_bf16 v[52:55], v[166:169], v[182:185], v[52:55]
	v_mfma_f32_16x16x32_bf16 v[48:51], v[174:177], v[182:185], v[48:51]
	v_mfma_f32_16x16x32_bf16 v[36:39], v[166:169], v[216:219], v[36:39]
	v_mfma_f32_16x16x32_bf16 v[32:35], v[174:177], v[216:219], v[32:35]
	v_mfma_f32_16x16x32_bf16 v[20:23], v[166:169], v[224:227], v[20:23]
	v_mfma_f32_16x16x32_bf16 v[16:19], v[174:177], v[224:227], v[16:19]
	v_mfma_f32_16x16x32_bf16 v[4:7], v[166:169], v[232:235], v[4:7]
	v_mfma_f32_16x16x32_bf16 v[0:3], v[174:177], v[232:235], v[0:3]
	s_setprio 0
	s_barrier
	s_add_u32 s66, s66, 0x100
	s_addc_u32 s67, s67, 0
	s_add_u32 s94, s94, 0x100
	s_addc_u32 s95, s95, 0
	s_cmp_ge_i32 vcc_lo, s55
	s_mov_b32 s82, vcc_lo
	s_cbranch_scc0 .LBB0_294
	s_mov_b64 s[88:89], 0x8000

.LBB0_316:
	s_add_i32 vcc_lo, s82, 2
	s_add_u32 s20, s66, 0xfffc0080
	s_addc_u32 s21, s67, -1
	s_add_i32 s52, 0, 0x10000
	s_cmp_eq_u32 s60, s82
	s_cselect_b32 s87, s39, s21
	s_cselect_b32 s86, s41, s20
	s_cselect_b32 s83, s88, s95
	s_cselect_b32 s82, s89, s94
	s_add_i32 s53, 0, 0x14000
	v_add_u32_e32 v156, s52, v142
	v_add_u32_e32 v172, s53, v142
	ds_read_b128 v[144:147], v156
	ds_read_b128 v[148:151], v156 offset:1024
	ds_read_b128 v[152:155], v156 offset:2048
	ds_read_b128 v[156:159], v156 offset:3072
	ds_read_b128 v[160:163], v172
	ds_read_b128 v[164:167], v172 offset:1024
	ds_read_b128 v[168:171], v172 offset:2048
	ds_read_b128 v[172:175], v172 offset:3072
	s_add_i32 m0, s13, 0xc000
	ds_read_b128 v[176:179], v143
	ds_read_b128 v[180:183], v143 offset:1024
	ds_read_b128 v[184:187], v143 offset:2048
	ds_read_b128 v[202:205], v143 offset:3072
	ds_read_b128 v[216:219], v143 offset:4096
	ds_read_b128 v[220:223], v143 offset:5120
	ds_read_b128 v[224:227], v143 offset:6144
	ds_read_b128 v[228:231], v143 offset:7168
	global_load_lds_dwordx4 v136, s[66:67]
	s_add_i32 m0, s13, 0xe000
	s_nop 0
	global_load_lds_dwordx4 v138, s[66:67]
	s_waitcnt vmcnt(8)
	s_waitcnt lgkmcnt(0)
	s_barrier
	s_setprio 1
	s_waitcnt lgkmcnt(0)
	v_mfma_f32_16x16x32_bf16 v[124:127], v[144:147], v[176:179], v[124:127]
	v_mfma_f32_16x16x32_bf16 v[120:123], v[152:155], v[176:179], v[120:123]
	v_mfma_f32_16x16x32_bf16 v[108:111], v[144:147], v[184:187], v[108:111]
	v_mfma_f32_16x16x32_bf16 v[104:107], v[152:155], v[184:187], v[104:107]
	v_mfma_f32_16x16x32_bf16 v[92:95], v[144:147], v[216:219], v[92:95]
	v_mfma_f32_16x16x32_bf16 v[88:91], v[152:155], v[216:219], v[88:91]
	v_mfma_f32_16x16x32_bf16 v[76:79], v[144:147], v[224:227], v[76:79]
	v_mfma_f32_16x16x32_bf16 v[72:75], v[152:155], v[224:227], v[72:75]
	v_mfma_f32_16x16x32_bf16 v[124:127], v[148:151], v[180:183], v[124:127]
	v_mfma_f32_16x16x32_bf16 v[120:123], v[156:159], v[180:183], v[120:123]
	v_mfma_f32_16x16x32_bf16 v[108:111], v[148:151], v[202:205], v[108:111]
	v_mfma_f32_16x16x32_bf16 v[104:107], v[156:159], v[202:205], v[104:107]
	v_mfma_f32_16x16x32_bf16 v[92:95], v[148:151], v[220:223], v[92:95]
	v_mfma_f32_16x16x32_bf16 v[88:91], v[156:159], v[220:223], v[88:91]
	v_mfma_f32_16x16x32_bf16 v[76:79], v[148:151], v[228:231], v[76:79]
	v_mfma_f32_16x16x32_bf16 v[72:75], v[156:159], v[228:231], v[72:75]
	s_setprio 0
	s_setprio 1
	v_mfma_f32_16x16x32_bf16 v[116:119], v[160:163], v[176:179], v[116:119]
	v_mfma_f32_16x16x32_bf16 v[112:115], v[168:171], v[176:179], v[112:115]
	v_mfma_f32_16x16x32_bf16 v[100:103], v[160:163], v[184:187], v[100:103]
	v_mfma_f32_16x16x32_bf16 v[96:99], v[168:171], v[184:187], v[96:99]
	v_mfma_f32_16x16x32_bf16 v[84:87], v[160:163], v[216:219], v[84:87]
	v_mfma_f32_16x16x32_bf16 v[80:83], v[168:171], v[216:219], v[80:83]
	v_mfma_f32_16x16x32_bf16 v[68:71], v[160:163], v[224:227], v[68:71]
	v_mfma_f32_16x16x32_bf16 v[64:67], v[168:171], v[224:227], v[64:67]
	v_mfma_f32_16x16x32_bf16 v[116:119], v[164:167], v[180:183], v[116:119]
	v_mfma_f32_16x16x32_bf16 v[112:115], v[172:175], v[180:183], v[112:115]
	v_mfma_f32_16x16x32_bf16 v[100:103], v[164:167], v[202:205], v[100:103]
	v_mfma_f32_16x16x32_bf16 v[96:99], v[172:175], v[202:205], v[96:99]
	v_mfma_f32_16x16x32_bf16 v[84:87], v[164:167], v[220:223], v[84:87]
	v_mfma_f32_16x16x32_bf16 v[80:83], v[172:175], v[220:223], v[80:83]
	v_mfma_f32_16x16x32_bf16 v[68:71], v[164:167], v[228:231], v[68:71]
	v_mfma_f32_16x16x32_bf16 v[64:67], v[172:175], v[228:231], v[64:67]
	s_setprio 0
	s_barrier
	s_add_i32 s20, s52, s12
	v_lshl_add_u64 v[194:195], s[82:83], 0, v[132:133]
	s_mov_b32 m0, s20
	ds_read_b128 v[176:179], v143 offset:16384
	ds_read_b128 v[180:183], v143 offset:17408
	ds_read_b128 v[184:187], v143 offset:18432
	ds_read_b128 v[202:205], v143 offset:19456
	ds_read_b128 v[216:219], v143 offset:20480
	ds_read_b128 v[220:223], v143 offset:21504
	ds_read_b128 v[224:227], v143 offset:22528
	ds_read_b128 v[228:231], v143 offset:23552
	global_load_lds_dwordx4 v[194:195], off
	s_add_i32 m0, s20, 0x2000
	s_add_u32 s20, s82, 0x40000
	v_lshl_add_u64 v[196:197], s[82:83], 0, v[128:129]
	s_addc_u32 s21, s83, 0
	s_add_i32 s52, s53, s12
	global_load_lds_dwordx4 v[196:197], off
	s_mov_b32 m0, s52
	v_lshl_add_u64 v[234:235], s[86:87], 0, v[130:131]
	global_load_lds_dwordx4 v132, s[20:21]
	s_add_i32 m0, s52, 0x2000
	s_nop 0
	global_load_lds_dwordx4 v128, s[20:21]
	v_lshl_add_u64 v[232:233], s[86:87], 0, v[134:135]
	s_mov_b32 m0, s13
	s_nop 0
	global_load_lds_dwordx4 v[232:233], off
	s_mov_b32 m0, s28
	s_nop 0
	global_load_lds_dwordx4 v[234:235], off
	s_waitcnt vmcnt(8)
	s_waitcnt lgkmcnt(0)
	s_barrier
	s_setprio 1
	s_waitcnt lgkmcnt(0)
	v_mfma_f32_16x16x32_bf16 v[60:63], v[144:147], v[176:179], v[60:63]
	v_mfma_f32_16x16x32_bf16 v[56:59], v[152:155], v[176:179], v[56:59]
	v_mfma_f32_16x16x32_bf16 v[44:47], v[144:147], v[184:187], v[44:47]
	v_mfma_f32_16x16x32_bf16 v[40:43], v[152:155], v[184:187], v[40:43]
	v_mfma_f32_16x16x32_bf16 v[28:31], v[144:147], v[216:219], v[28:31]
	v_mfma_f32_16x16x32_bf16 v[24:27], v[152:155], v[216:219], v[24:27]
	v_mfma_f32_16x16x32_bf16 v[12:15], v[144:147], v[224:227], v[12:15]
	v_mfma_f32_16x16x32_bf16 v[8:11], v[152:155], v[224:227], v[8:11]
	v_mfma_f32_16x16x32_bf16 v[60:63], v[148:151], v[180:183], v[60:63]
	v_mfma_f32_16x16x32_bf16 v[56:59], v[156:159], v[180:183], v[56:59]
	v_mfma_f32_16x16x32_bf16 v[44:47], v[148:151], v[202:205], v[44:47]
	v_mfma_f32_16x16x32_bf16 v[40:43], v[156:159], v[202:205], v[40:43]
	v_mfma_f32_16x16x32_bf16 v[28:31], v[148:151], v[220:223], v[28:31]
	v_mfma_f32_16x16x32_bf16 v[24:27], v[156:159], v[220:223], v[24:27]
	v_mfma_f32_16x16x32_bf16 v[12:15], v[148:151], v[228:231], v[12:15]
	v_mfma_f32_16x16x32_bf16 v[8:11], v[156:159], v[228:231], v[8:11]
	s_setprio 0
	s_setprio 1
	v_mfma_f32_16x16x32_bf16 v[52:55], v[160:163], v[176:179], v[52:55]
	v_mfma_f32_16x16x32_bf16 v[48:51], v[168:171], v[176:179], v[48:51]
	v_mfma_f32_16x16x32_bf16 v[36:39], v[160:163], v[184:187], v[36:39]
	v_mfma_f32_16x16x32_bf16 v[32:35], v[168:171], v[184:187], v[32:35]
	v_mfma_f32_16x16x32_bf16 v[20:23], v[160:163], v[216:219], v[20:23]
	v_mfma_f32_16x16x32_bf16 v[16:19], v[168:171], v[216:219], v[16:19]
	v_mfma_f32_16x16x32_bf16 v[4:7], v[160:163], v[224:227], v[4:7]
	v_mfma_f32_16x16x32_bf16 v[0:3], v[168:171], v[224:227], v[0:3]
	v_mfma_f32_16x16x32_bf16 v[52:55], v[164:167], v[180:183], v[52:55]
	v_mfma_f32_16x16x32_bf16 v[48:51], v[172:175], v[180:183], v[48:51]
	v_mfma_f32_16x16x32_bf16 v[36:39], v[164:167], v[202:205], v[36:39]
	v_mfma_f32_16x16x32_bf16 v[32:35], v[172:175], v[202:205], v[32:35]
	v_mfma_f32_16x16x32_bf16 v[20:23], v[164:167], v[220:223], v[20:23]
	v_mfma_f32_16x16x32_bf16 v[16:19], v[172:175], v[220:223], v[16:19]
	v_mfma_f32_16x16x32_bf16 v[4:7], v[164:167], v[228:231], v[4:7]
	v_mfma_f32_16x16x32_bf16 v[0:3], v[172:175], v[228:231], v[0:3]
	s_setprio 0
	s_barrier
	s_add_i32 s52, 0, 0x18000
	s_add_i32 s53, 0, 0x1c000
	v_add_u32_e32 v156, s52, v142
	v_add_u32_e32 v172, s53, v142
	ds_read_b128 v[144:147], v156
	ds_read_b128 v[148:151], v156 offset:1024
	ds_read_b128 v[152:155], v156 offset:2048
	ds_read_b128 v[156:159], v156 offset:3072
	ds_read_b128 v[160:163], v172
	ds_read_b128 v[164:167], v172 offset:1024
	ds_read_b128 v[168:171], v172 offset:2048
	ds_read_b128 v[172:175], v172 offset:3072
	s_add_u32 s20, s86, 0x40000
	s_addc_u32 s21, s87, 0
	s_mov_b32 m0, s46
	ds_read_b128 v[176:179], v143 offset:32768
	ds_read_b128 v[180:183], v143 offset:33792
	ds_read_b128 v[184:187], v143 offset:34816
	ds_read_b128 v[202:205], v143 offset:35840
	ds_read_b128 v[216:219], v143 offset:36864
	ds_read_b128 v[220:223], v143 offset:37888
	ds_read_b128 v[224:227], v143 offset:38912
	ds_read_b128 v[228:231], v143 offset:39936
	global_load_lds_dwordx4 v134, s[20:21]
	s_mov_b32 m0, s47
	s_nop 0
	global_load_lds_dwordx4 v130, s[20:21]
	s_waitcnt vmcnt(8)
	s_waitcnt lgkmcnt(0)
	s_barrier
	s_setprio 1
	s_waitcnt lgkmcnt(0)
	v_mfma_f32_16x16x32_bf16 v[124:127], v[144:147], v[176:179], v[124:127]
	v_mfma_f32_16x16x32_bf16 v[120:123], v[152:155], v[176:179], v[120:123]
	v_mfma_f32_16x16x32_bf16 v[108:111], v[144:147], v[184:187], v[108:111]
	v_mfma_f32_16x16x32_bf16 v[104:107], v[152:155], v[184:187], v[104:107]
	v_mfma_f32_16x16x32_bf16 v[92:95], v[144:147], v[216:219], v[92:95]
	v_mfma_f32_16x16x32_bf16 v[88:91], v[152:155], v[216:219], v[88:91]
	v_mfma_f32_16x16x32_bf16 v[76:79], v[144:147], v[224:227], v[76:79]
	v_mfma_f32_16x16x32_bf16 v[72:75], v[152:155], v[224:227], v[72:75]
	v_mfma_f32_16x16x32_bf16 v[124:127], v[148:151], v[180:183], v[124:127]
	v_mfma_f32_16x16x32_bf16 v[120:123], v[156:159], v[180:183], v[120:123]
	v_mfma_f32_16x16x32_bf16 v[108:111], v[148:151], v[202:205], v[108:111]
	v_mfma_f32_16x16x32_bf16 v[104:107], v[156:159], v[202:205], v[104:107]
	v_mfma_f32_16x16x32_bf16 v[92:95], v[148:151], v[220:223], v[92:95]
	v_mfma_f32_16x16x32_bf16 v[88:91], v[156:159], v[220:223], v[88:91]
	v_mfma_f32_16x16x32_bf16 v[76:79], v[148:151], v[228:231], v[76:79]
	v_mfma_f32_16x16x32_bf16 v[72:75], v[156:159], v[228:231], v[72:75]
	s_setprio 0
	s_setprio 1
	v_mfma_f32_16x16x32_bf16 v[116:119], v[160:163], v[176:179], v[116:119]
	v_mfma_f32_16x16x32_bf16 v[112:115], v[168:171], v[176:179], v[112:115]
	v_mfma_f32_16x16x32_bf16 v[100:103], v[160:163], v[184:187], v[100:103]
	v_mfma_f32_16x16x32_bf16 v[96:99], v[168:171], v[184:187], v[96:99]
	v_mfma_f32_16x16x32_bf16 v[84:87], v[160:163], v[216:219], v[84:87]
	v_mfma_f32_16x16x32_bf16 v[80:83], v[168:171], v[216:219], v[80:83]
	v_mfma_f32_16x16x32_bf16 v[68:71], v[160:163], v[224:227], v[68:71]
	v_mfma_f32_16x16x32_bf16 v[64:67], v[168:171], v[224:227], v[64:67]
	v_mfma_f32_16x16x32_bf16 v[116:119], v[164:167], v[180:183], v[116:119]
	v_mfma_f32_16x16x32_bf16 v[112:115], v[172:175], v[180:183], v[112:115]
	v_mfma_f32_16x16x32_bf16 v[100:103], v[164:167], v[202:205], v[100:103]
	v_mfma_f32_16x16x32_bf16 v[96:99], v[172:175], v[202:205], v[96:99]
	v_mfma_f32_16x16x32_bf16 v[84:87], v[164:167], v[220:223], v[84:87]
	v_mfma_f32_16x16x32_bf16 v[80:83], v[172:175], v[220:223], v[80:83]
	v_mfma_f32_16x16x32_bf16 v[68:71], v[164:167], v[228:231], v[68:71]
	v_mfma_f32_16x16x32_bf16 v[64:67], v[172:175], v[228:231], v[64:67]
	s_setprio 0
	s_barrier
	s_add_i32 s20, s52, s12
	v_lshl_add_u64 v[194:195], v[194:195], 0, s[62:63]
	s_mov_b32 m0, s20
	ds_read_b128 v[176:179], v143 offset:49152
	ds_read_b128 v[180:183], v143 offset:50176
	ds_read_b128 v[184:187], v143 offset:51200
	ds_read_b128 v[202:205], v143 offset:52224
	ds_read_b128 v[216:219], v143 offset:53248
	ds_read_b128 v[220:223], v143 offset:54272
	ds_read_b128 v[224:227], v143 offset:55296
	ds_read_b128 v[228:231], v143 offset:56320
	global_load_lds_dwordx4 v[194:195], off
	s_add_i32 m0, s20, 0x2000
	s_add_u32 s20, s82, 0x40080
	v_lshl_add_u64 v[194:195], v[196:197], 0, s[62:63]
	s_addc_u32 s21, s83, 0
	s_add_i32 s52, s53, s12
	global_load_lds_dwordx4 v[194:195], off
	s_mov_b32 m0, s52
	s_nop 0
	global_load_lds_dwordx4 v132, s[20:21]
	s_add_i32 m0, s52, 0x2000
	s_nop 0
	global_load_lds_dwordx4 v128, s[20:21]
	v_lshl_add_u64 v[194:195], v[232:233], 0, s[62:63]
	s_mov_b32 m0, s56
	s_nop 0
	global_load_lds_dwordx4 v[194:195], off
	v_lshl_add_u64 v[194:195], v[234:235], 0, s[62:63]
	s_mov_b32 m0, s57
	s_nop 0
	global_load_lds_dwordx4 v[194:195], off
	s_waitcnt vmcnt(8)
	s_waitcnt lgkmcnt(0)
	s_barrier
	s_setprio 1
	s_waitcnt lgkmcnt(0)
	v_mfma_f32_16x16x32_bf16 v[60:63], v[144:147], v[176:179], v[60:63]
	v_mfma_f32_16x16x32_bf16 v[56:59], v[152:155], v[176:179], v[56:59]
	v_mfma_f32_16x16x32_bf16 v[44:47], v[144:147], v[184:187], v[44:47]
	v_mfma_f32_16x16x32_bf16 v[40:43], v[152:155], v[184:187], v[40:43]
	v_mfma_f32_16x16x32_bf16 v[28:31], v[144:147], v[216:219], v[28:31]
	v_mfma_f32_16x16x32_bf16 v[24:27], v[152:155], v[216:219], v[24:27]
	v_mfma_f32_16x16x32_bf16 v[12:15], v[144:147], v[224:227], v[12:15]
	v_mfma_f32_16x16x32_bf16 v[8:11], v[152:155], v[224:227], v[8:11]
	v_mfma_f32_16x16x32_bf16 v[60:63], v[148:151], v[180:183], v[60:63]
	v_mfma_f32_16x16x32_bf16 v[56:59], v[156:159], v[180:183], v[56:59]
	v_mfma_f32_16x16x32_bf16 v[44:47], v[148:151], v[202:205], v[44:47]
	v_mfma_f32_16x16x32_bf16 v[40:43], v[156:159], v[202:205], v[40:43]
	v_mfma_f32_16x16x32_bf16 v[28:31], v[148:151], v[220:223], v[28:31]
	v_mfma_f32_16x16x32_bf16 v[24:27], v[156:159], v[220:223], v[24:27]
	v_mfma_f32_16x16x32_bf16 v[12:15], v[148:151], v[228:231], v[12:15]
	v_mfma_f32_16x16x32_bf16 v[8:11], v[156:159], v[228:231], v[8:11]
	s_setprio 0
	s_setprio 1
	v_mfma_f32_16x16x32_bf16 v[52:55], v[160:163], v[176:179], v[52:55]
	v_mfma_f32_16x16x32_bf16 v[48:51], v[168:171], v[176:179], v[48:51]
	v_mfma_f32_16x16x32_bf16 v[36:39], v[160:163], v[184:187], v[36:39]
	v_mfma_f32_16x16x32_bf16 v[32:35], v[168:171], v[184:187], v[32:35]
	v_mfma_f32_16x16x32_bf16 v[20:23], v[160:163], v[216:219], v[20:23]
	v_mfma_f32_16x16x32_bf16 v[16:19], v[168:171], v[216:219], v[16:19]
	v_mfma_f32_16x16x32_bf16 v[4:7], v[160:163], v[224:227], v[4:7]
	v_mfma_f32_16x16x32_bf16 v[0:3], v[168:171], v[224:227], v[0:3]
	v_mfma_f32_16x16x32_bf16 v[52:55], v[164:167], v[180:183], v[52:55]
	v_mfma_f32_16x16x32_bf16 v[48:51], v[172:175], v[180:183], v[48:51]
	v_mfma_f32_16x16x32_bf16 v[36:39], v[164:167], v[202:205], v[36:39]
	v_mfma_f32_16x16x32_bf16 v[32:35], v[172:175], v[202:205], v[32:35]
	v_mfma_f32_16x16x32_bf16 v[20:23], v[164:167], v[220:223], v[20:23]
	v_mfma_f32_16x16x32_bf16 v[16:19], v[172:175], v[220:223], v[16:19]
	v_mfma_f32_16x16x32_bf16 v[4:7], v[164:167], v[228:231], v[4:7]
	v_mfma_f32_16x16x32_bf16 v[0:3], v[172:175], v[228:231], v[0:3]
	s_setprio 0
	s_barrier
	s_add_u32 s66, s66, 0x100
	s_addc_u32 s67, s67, 0
	s_add_u32 s94, s94, 0x100
	s_addc_u32 s95, s95, 0
	s_cmp_ge_i32 vcc_lo, s48
	s_mov_b32 s82, vcc_lo
	s_cbranch_scc0 .LBB0_316
	s_mov_b64 s[88:89], 0x8000

.LBB0_578:
	s_add_i32 s95, s42, 2
	s_add_u32 s43, s40, 0xfffc0080
	s_addc_u32 s56, s41, -1
	s_add_i32 vcc_lo, 0, 0x10000
	s_cmp_eq_u32 s87, s42
	s_cselect_b32 s57, s49, s56
	s_cselect_b32 s56, s51, s43
	s_cselect_b32 s43, s59, s94
	s_cselect_b32 s42, s88, s89
	s_add_i32 s36, 0, 0x14000
	v_add_u32_e32 v150, vcc_lo, v156
	v_add_u32_e32 v170, s36, v156
	ds_read_b128 v[128:131], v150
	ds_read_b128 v[132:135], v150 offset:1024
	ds_read_b128 v[146:149], v150 offset:2048
	ds_read_b128 v[150:153], v150 offset:3072
	ds_read_b128 v[158:161], v170
	ds_read_b128 v[162:165], v170 offset:1024
	ds_read_b128 v[166:169], v170 offset:2048
	ds_read_b128 v[170:173], v170 offset:3072
	s_add_i32 m0, s5, 0xc000
	ds_read_b128 v[174:177], v157
	ds_read_b128 v[178:181], v157 offset:1024
	ds_read_b128 v[182:185], v157 offset:2048
	ds_read_b128 v[194:197], v157 offset:3072
	ds_read_b128 v[202:205], v157 offset:4096
	ds_read_b128 v[216:219], v157 offset:5120
	ds_read_b128 v[220:223], v157 offset:6144
	ds_read_b128 v[224:227], v157 offset:7168
	global_load_lds_dwordx4 v142, s[40:41]
	s_add_i32 m0, s5, 0xe000
	s_nop 0
	global_load_lds_dwordx4 v144, s[40:41]
	s_waitcnt vmcnt(8)
	s_waitcnt lgkmcnt(0)
	s_barrier
	s_setprio 1
	s_waitcnt lgkmcnt(0)
	v_mfma_f32_16x16x32_bf16 v[124:127], v[128:131], v[174:177], v[124:127]
	v_mfma_f32_16x16x32_bf16 v[120:123], v[146:149], v[174:177], v[120:123]
	v_mfma_f32_16x16x32_bf16 v[108:111], v[128:131], v[182:185], v[108:111]
	v_mfma_f32_16x16x32_bf16 v[104:107], v[146:149], v[182:185], v[104:107]
	v_mfma_f32_16x16x32_bf16 v[92:95], v[128:131], v[202:205], v[92:95]
	v_mfma_f32_16x16x32_bf16 v[88:91], v[146:149], v[202:205], v[88:91]
	v_mfma_f32_16x16x32_bf16 v[76:79], v[128:131], v[220:223], v[76:79]
	v_mfma_f32_16x16x32_bf16 v[72:75], v[146:149], v[220:223], v[72:75]
	v_mfma_f32_16x16x32_bf16 v[124:127], v[132:135], v[178:181], v[124:127]
	v_mfma_f32_16x16x32_bf16 v[120:123], v[150:153], v[178:181], v[120:123]
	v_mfma_f32_16x16x32_bf16 v[108:111], v[132:135], v[194:197], v[108:111]
	v_mfma_f32_16x16x32_bf16 v[104:107], v[150:153], v[194:197], v[104:107]
	v_mfma_f32_16x16x32_bf16 v[92:95], v[132:135], v[216:219], v[92:95]
	v_mfma_f32_16x16x32_bf16 v[88:91], v[150:153], v[216:219], v[88:91]
	v_mfma_f32_16x16x32_bf16 v[76:79], v[132:135], v[224:227], v[76:79]
	v_mfma_f32_16x16x32_bf16 v[72:75], v[150:153], v[224:227], v[72:75]
	s_setprio 0
	s_setprio 1
	v_mfma_f32_16x16x32_bf16 v[116:119], v[158:161], v[174:177], v[116:119]
	v_mfma_f32_16x16x32_bf16 v[112:115], v[166:169], v[174:177], v[112:115]
	v_mfma_f32_16x16x32_bf16 v[100:103], v[158:161], v[182:185], v[100:103]
	v_mfma_f32_16x16x32_bf16 v[96:99], v[166:169], v[182:185], v[96:99]
	v_mfma_f32_16x16x32_bf16 v[84:87], v[158:161], v[202:205], v[84:87]
	v_mfma_f32_16x16x32_bf16 v[80:83], v[166:169], v[202:205], v[80:83]
	v_mfma_f32_16x16x32_bf16 v[68:71], v[158:161], v[220:223], v[68:71]
	v_mfma_f32_16x16x32_bf16 v[64:67], v[166:169], v[220:223], v[64:67]
	v_mfma_f32_16x16x32_bf16 v[116:119], v[162:165], v[178:181], v[116:119]
	v_mfma_f32_16x16x32_bf16 v[112:115], v[170:173], v[178:181], v[112:115]
	v_mfma_f32_16x16x32_bf16 v[100:103], v[162:165], v[194:197], v[100:103]
	v_mfma_f32_16x16x32_bf16 v[96:99], v[170:173], v[194:197], v[96:99]
	v_mfma_f32_16x16x32_bf16 v[84:87], v[162:165], v[216:219], v[84:87]
	v_mfma_f32_16x16x32_bf16 v[80:83], v[170:173], v[216:219], v[80:83]
	v_mfma_f32_16x16x32_bf16 v[68:71], v[162:165], v[224:227], v[68:71]
	v_mfma_f32_16x16x32_bf16 v[64:67], v[170:173], v[224:227], v[64:67]
	s_setprio 0
	s_barrier
	s_add_i32 s37, vcc_lo, s60
	v_lshl_add_u64 v[186:187], s[42:43], 0, v[188:189]
	s_mov_b32 m0, s37
	ds_read_b128 v[174:177], v157 offset:16384
	ds_read_b128 v[178:181], v157 offset:17408
	ds_read_b128 v[182:185], v157 offset:18432
	ds_read_b128 v[194:197], v157 offset:19456
	ds_read_b128 v[202:205], v157 offset:20480
	ds_read_b128 v[216:219], v157 offset:21504
	ds_read_b128 v[220:223], v157 offset:22528
	ds_read_b128 v[224:227], v157 offset:23552
	global_load_lds_dwordx4 v[186:187], off
	s_add_i32 m0, s37, 0x2000
	s_add_u32 vcc_lo, s42, 0x40000
	v_lshl_add_u64 v[228:229], s[42:43], 0, v[136:137]
	s_addc_u32 vcc_hi, s43, 0
	s_add_i32 s36, s36, s60
	global_load_lds_dwordx4 v[228:229], off
	s_mov_b32 m0, s36
	v_lshl_add_u64 v[232:233], s[56:57], 0, v[138:139]
	global_load_lds_dwordx4 v188, vcc
	s_add_i32 m0, s36, 0x2000
	s_nop 0
	global_load_lds_dwordx4 v136, vcc
	v_lshl_add_u64 v[230:231], s[56:57], 0, v[140:141]
	s_mov_b32 m0, s5
	s_nop 0
	global_load_lds_dwordx4 v[230:231], off
	s_mov_b32 m0, s6
	s_nop 0
	global_load_lds_dwordx4 v[232:233], off
	s_waitcnt vmcnt(8)
	s_waitcnt lgkmcnt(0)
	s_barrier
	s_setprio 1
	s_waitcnt lgkmcnt(0)
	v_mfma_f32_16x16x32_bf16 v[60:63], v[128:131], v[174:177], v[60:63]
	v_mfma_f32_16x16x32_bf16 v[56:59], v[146:149], v[174:177], v[56:59]
	v_mfma_f32_16x16x32_bf16 v[44:47], v[128:131], v[182:185], v[44:47]
	v_mfma_f32_16x16x32_bf16 v[40:43], v[146:149], v[182:185], v[40:43]
	v_mfma_f32_16x16x32_bf16 v[28:31], v[128:131], v[202:205], v[28:31]
	v_mfma_f32_16x16x32_bf16 v[24:27], v[146:149], v[202:205], v[24:27]
	v_mfma_f32_16x16x32_bf16 v[12:15], v[128:131], v[220:223], v[12:15]
	v_mfma_f32_16x16x32_bf16 v[8:11], v[146:149], v[220:223], v[8:11]
	v_mfma_f32_16x16x32_bf16 v[60:63], v[132:135], v[178:181], v[60:63]
	v_mfma_f32_16x16x32_bf16 v[56:59], v[150:153], v[178:181], v[56:59]
	v_mfma_f32_16x16x32_bf16 v[44:47], v[132:135], v[194:197], v[44:47]
	v_mfma_f32_16x16x32_bf16 v[40:43], v[150:153], v[194:197], v[40:43]
	v_mfma_f32_16x16x32_bf16 v[28:31], v[132:135], v[216:219], v[28:31]
	v_mfma_f32_16x16x32_bf16 v[24:27], v[150:153], v[216:219], v[24:27]
	v_mfma_f32_16x16x32_bf16 v[12:15], v[132:135], v[224:227], v[12:15]
	v_mfma_f32_16x16x32_bf16 v[8:11], v[150:153], v[224:227], v[8:11]
	s_setprio 0
	s_setprio 1
	v_mfma_f32_16x16x32_bf16 v[52:55], v[158:161], v[174:177], v[52:55]
	v_mfma_f32_16x16x32_bf16 v[48:51], v[166:169], v[174:177], v[48:51]
	v_mfma_f32_16x16x32_bf16 v[36:39], v[158:161], v[182:185], v[36:39]
	v_mfma_f32_16x16x32_bf16 v[32:35], v[166:169], v[182:185], v[32:35]
	v_mfma_f32_16x16x32_bf16 v[20:23], v[158:161], v[202:205], v[20:23]
	v_mfma_f32_16x16x32_bf16 v[16:19], v[166:169], v[202:205], v[16:19]
	v_mfma_f32_16x16x32_bf16 v[4:7], v[158:161], v[220:223], v[4:7]
	v_mfma_f32_16x16x32_bf16 v[0:3], v[166:169], v[220:223], v[0:3]
	v_mfma_f32_16x16x32_bf16 v[52:55], v[162:165], v[178:181], v[52:55]
	v_mfma_f32_16x16x32_bf16 v[48:51], v[170:173], v[178:181], v[48:51]
	v_mfma_f32_16x16x32_bf16 v[36:39], v[162:165], v[194:197], v[36:39]
	v_mfma_f32_16x16x32_bf16 v[32:35], v[170:173], v[194:197], v[32:35]
	v_mfma_f32_16x16x32_bf16 v[20:23], v[162:165], v[216:219], v[20:23]
	v_mfma_f32_16x16x32_bf16 v[16:19], v[170:173], v[216:219], v[16:19]
	v_mfma_f32_16x16x32_bf16 v[4:7], v[162:165], v[224:227], v[4:7]
	v_mfma_f32_16x16x32_bf16 v[0:3], v[170:173], v[224:227], v[0:3]
	s_setprio 0
	s_barrier
	s_add_i32 s36, 0, 0x18000
	s_add_i32 s37, 0, 0x1c000
	v_add_u32_e32 v150, s36, v156
	v_add_u32_e32 v170, s37, v156
	ds_read_b128 v[128:131], v150
	ds_read_b128 v[132:135], v150 offset:1024
	ds_read_b128 v[146:149], v150 offset:2048
	ds_read_b128 v[150:153], v150 offset:3072
	ds_read_b128 v[158:161], v170
	ds_read_b128 v[162:165], v170 offset:1024
	ds_read_b128 v[166:169], v170 offset:2048
	ds_read_b128 v[170:173], v170 offset:3072
	s_add_u32 s56, s56, 0x40000
	s_addc_u32 s57, s57, 0
	s_mov_b32 m0, s7
	ds_read_b128 v[174:177], v157 offset:32768
	ds_read_b128 v[178:181], v157 offset:33792
	ds_read_b128 v[182:185], v157 offset:34816
	ds_read_b128 v[194:197], v157 offset:35840
	ds_read_b128 v[202:205], v157 offset:36864
	ds_read_b128 v[216:219], v157 offset:37888
	ds_read_b128 v[220:223], v157 offset:38912
	ds_read_b128 v[224:227], v157 offset:39936
	global_load_lds_dwordx4 v140, s[56:57]
	s_mov_b32 m0, s8
	s_nop 0
	global_load_lds_dwordx4 v138, s[56:57]
	s_waitcnt vmcnt(8)
	s_waitcnt lgkmcnt(0)
	s_barrier
	s_setprio 1
	s_waitcnt lgkmcnt(0)
	v_mfma_f32_16x16x32_bf16 v[124:127], v[128:131], v[174:177], v[124:127]
	v_mfma_f32_16x16x32_bf16 v[120:123], v[146:149], v[174:177], v[120:123]
	v_mfma_f32_16x16x32_bf16 v[108:111], v[128:131], v[182:185], v[108:111]
	v_mfma_f32_16x16x32_bf16 v[104:107], v[146:149], v[182:185], v[104:107]
	v_mfma_f32_16x16x32_bf16 v[92:95], v[128:131], v[202:205], v[92:95]
	v_mfma_f32_16x16x32_bf16 v[88:91], v[146:149], v[202:205], v[88:91]
	v_mfma_f32_16x16x32_bf16 v[76:79], v[128:131], v[220:223], v[76:79]
	v_mfma_f32_16x16x32_bf16 v[72:75], v[146:149], v[220:223], v[72:75]
	v_mfma_f32_16x16x32_bf16 v[124:127], v[132:135], v[178:181], v[124:127]
	v_mfma_f32_16x16x32_bf16 v[120:123], v[150:153], v[178:181], v[120:123]
	v_mfma_f32_16x16x32_bf16 v[108:111], v[132:135], v[194:197], v[108:111]
	v_mfma_f32_16x16x32_bf16 v[104:107], v[150:153], v[194:197], v[104:107]
	v_mfma_f32_16x16x32_bf16 v[92:95], v[132:135], v[216:219], v[92:95]
	v_mfma_f32_16x16x32_bf16 v[88:91], v[150:153], v[216:219], v[88:91]
	v_mfma_f32_16x16x32_bf16 v[76:79], v[132:135], v[224:227], v[76:79]
	v_mfma_f32_16x16x32_bf16 v[72:75], v[150:153], v[224:227], v[72:75]
	s_setprio 0
	s_setprio 1
	v_mfma_f32_16x16x32_bf16 v[116:119], v[158:161], v[174:177], v[116:119]
	v_mfma_f32_16x16x32_bf16 v[112:115], v[166:169], v[174:177], v[112:115]
	v_mfma_f32_16x16x32_bf16 v[100:103], v[158:161], v[182:185], v[100:103]
	v_mfma_f32_16x16x32_bf16 v[96:99], v[166:169], v[182:185], v[96:99]
	v_mfma_f32_16x16x32_bf16 v[84:87], v[158:161], v[202:205], v[84:87]
	v_mfma_f32_16x16x32_bf16 v[80:83], v[166:169], v[202:205], v[80:83]
	v_mfma_f32_16x16x32_bf16 v[68:71], v[158:161], v[220:223], v[68:71]
	v_mfma_f32_16x16x32_bf16 v[64:67], v[166:169], v[220:223], v[64:67]
	v_mfma_f32_16x16x32_bf16 v[116:119], v[162:165], v[178:181], v[116:119]
	v_mfma_f32_16x16x32_bf16 v[112:115], v[170:173], v[178:181], v[112:115]
	v_mfma_f32_16x16x32_bf16 v[100:103], v[162:165], v[194:197], v[100:103]
	v_mfma_f32_16x16x32_bf16 v[96:99], v[170:173], v[194:197], v[96:99]
	v_mfma_f32_16x16x32_bf16 v[84:87], v[162:165], v[216:219], v[84:87]
	v_mfma_f32_16x16x32_bf16 v[80:83], v[170:173], v[216:219], v[80:83]
	v_mfma_f32_16x16x32_bf16 v[68:71], v[162:165], v[224:227], v[68:71]
	v_mfma_f32_16x16x32_bf16 v[64:67], v[170:173], v[224:227], v[64:67]
	s_setprio 0
	s_barrier
	s_add_i32 s36, s36, s60
	v_lshl_add_u64 v[186:187], v[186:187], 0, s[62:63]
	s_mov_b32 m0, s36
	ds_read_b128 v[174:177], v157 offset:49152
	ds_read_b128 v[178:181], v157 offset:50176
	ds_read_b128 v[182:185], v157 offset:51200
	ds_read_b128 v[194:197], v157 offset:52224
	ds_read_b128 v[202:205], v157 offset:53248
	ds_read_b128 v[216:219], v157 offset:54272
	ds_read_b128 v[220:223], v157 offset:55296
	ds_read_b128 v[224:227], v157 offset:56320
	global_load_lds_dwordx4 v[186:187], off
	s_add_i32 m0, s36, 0x2000
	s_add_u32 s42, s42, 0x40080
	v_lshl_add_u64 v[186:187], v[228:229], 0, s[62:63]
	s_addc_u32 s43, s43, 0
	s_add_i32 s36, s37, s60
	global_load_lds_dwordx4 v[186:187], off
	s_mov_b32 m0, s36
	s_nop 0
	global_load_lds_dwordx4 v188, s[42:43]
	s_add_i32 m0, s36, 0x2000
	s_nop 0
	global_load_lds_dwordx4 v136, s[42:43]
	v_lshl_add_u64 v[186:187], v[230:231], 0, s[62:63]
	s_mov_b32 m0, s85
	s_nop 0
	global_load_lds_dwordx4 v[186:187], off
	v_lshl_add_u64 v[186:187], v[232:233], 0, s[62:63]
	s_mov_b32 m0, s86
	s_nop 0
	global_load_lds_dwordx4 v[186:187], off
	s_waitcnt vmcnt(8)
	s_waitcnt lgkmcnt(0)
	s_barrier
	s_setprio 1
	s_waitcnt lgkmcnt(0)
	v_mfma_f32_16x16x32_bf16 v[60:63], v[128:131], v[174:177], v[60:63]
	v_mfma_f32_16x16x32_bf16 v[56:59], v[146:149], v[174:177], v[56:59]
	v_mfma_f32_16x16x32_bf16 v[44:47], v[128:131], v[182:185], v[44:47]
	v_mfma_f32_16x16x32_bf16 v[40:43], v[146:149], v[182:185], v[40:43]
	v_mfma_f32_16x16x32_bf16 v[28:31], v[128:131], v[202:205], v[28:31]
	v_mfma_f32_16x16x32_bf16 v[24:27], v[146:149], v[202:205], v[24:27]
	v_mfma_f32_16x16x32_bf16 v[12:15], v[128:131], v[220:223], v[12:15]
	v_mfma_f32_16x16x32_bf16 v[8:11], v[146:149], v[220:223], v[8:11]
	v_mfma_f32_16x16x32_bf16 v[60:63], v[132:135], v[178:181], v[60:63]
	v_mfma_f32_16x16x32_bf16 v[56:59], v[150:153], v[178:181], v[56:59]
	v_mfma_f32_16x16x32_bf16 v[44:47], v[132:135], v[194:197], v[44:47]
	v_mfma_f32_16x16x32_bf16 v[40:43], v[150:153], v[194:197], v[40:43]
	v_mfma_f32_16x16x32_bf16 v[28:31], v[132:135], v[216:219], v[28:31]
	v_mfma_f32_16x16x32_bf16 v[24:27], v[150:153], v[216:219], v[24:27]
	v_mfma_f32_16x16x32_bf16 v[12:15], v[132:135], v[224:227], v[12:15]
	v_mfma_f32_16x16x32_bf16 v[8:11], v[150:153], v[224:227], v[8:11]
	s_setprio 0
	s_setprio 1
	v_mfma_f32_16x16x32_bf16 v[52:55], v[158:161], v[174:177], v[52:55]
	v_mfma_f32_16x16x32_bf16 v[48:51], v[166:169], v[174:177], v[48:51]
	v_mfma_f32_16x16x32_bf16 v[36:39], v[158:161], v[182:185], v[36:39]
	v_mfma_f32_16x16x32_bf16 v[32:35], v[166:169], v[182:185], v[32:35]
	v_mfma_f32_16x16x32_bf16 v[20:23], v[158:161], v[202:205], v[20:23]
	v_mfma_f32_16x16x32_bf16 v[16:19], v[166:169], v[202:205], v[16:19]
	v_mfma_f32_16x16x32_bf16 v[4:7], v[158:161], v[220:223], v[4:7]
	v_mfma_f32_16x16x32_bf16 v[0:3], v[166:169], v[220:223], v[0:3]
	v_mfma_f32_16x16x32_bf16 v[52:55], v[162:165], v[178:181], v[52:55]
	v_mfma_f32_16x16x32_bf16 v[48:51], v[170:173], v[178:181], v[48:51]
	v_mfma_f32_16x16x32_bf16 v[36:39], v[162:165], v[194:197], v[36:39]
	v_mfma_f32_16x16x32_bf16 v[32:35], v[170:173], v[194:197], v[32:35]
	v_mfma_f32_16x16x32_bf16 v[20:23], v[162:165], v[216:219], v[20:23]
	v_mfma_f32_16x16x32_bf16 v[16:19], v[170:173], v[216:219], v[16:19]
	v_mfma_f32_16x16x32_bf16 v[4:7], v[162:165], v[224:227], v[4:7]
	v_mfma_f32_16x16x32_bf16 v[0:3], v[170:173], v[224:227], v[0:3]
	s_setprio 0
	s_barrier
	s_add_u32 s40, s40, 0x100
	s_addc_u32 s41, s41, 0
	s_add_u32 s89, s89, 0x100
	s_addc_u32 s94, s94, 0
	s_cmp_ge_i32 s95, s81
	s_mov_b32 s42, s95
	s_cbranch_scc0 .LBB0_578

.LBB0_734:
	s_add_i32 s85, s48, 2
	s_add_u32 s49, s38, 0xfffc0080
	s_addc_u32 s50, s39, -1
	s_add_i32 s86, 0, 0x10000
	s_cmp_eq_u32 s70, s48
	s_cselect_b32 s51, s41, s50
	s_cselect_b32 s50, s43, s49
	v_add_u32_e32 v146, s86, v150
	s_cselect_b32 s49, s81, s84
	s_cselect_b32 s48, s82, s83
	s_add_i32 s88, 0, 0x14000
	ds_read_b128 v[138:141], v146
	ds_read_b128 v[142:145], v146 offset:1024
	ds_read_b128 v[152:155], v146 offset:2048
	ds_read_b128 v[156:159], v146 offset:3072
	v_add_u32_e32 v146, s88, v150
	ds_read_b128 v[160:163], v146
	ds_read_b128 v[164:167], v146 offset:1024
	ds_read_b128 v[168:171], v146 offset:2048
	ds_read_b128 v[172:175], v146 offset:3072
	s_add_i32 m0, s55, 0xc000
	ds_read_b128 v[176:179], v151
	ds_read_b128 v[180:183], v151 offset:1024
	ds_read_b128 v[184:187], v151 offset:2048
	ds_read_b128 v[194:197], v151 offset:3072
	ds_read_b128 v[202:205], v151 offset:4096
	ds_read_b128 v[216:219], v151 offset:5120
	ds_read_b128 v[220:223], v151 offset:6144
	ds_read_b128 v[224:227], v151 offset:7168
	global_load_lds_dwordx4 v134, s[38:39]
	s_add_i32 m0, s55, 0xe000
	s_nop 0
	global_load_lds_dwordx4 v136, s[38:39]
	s_waitcnt vmcnt(8)
	s_waitcnt lgkmcnt(0)
	s_barrier
	s_setprio 1
	s_waitcnt lgkmcnt(0)
	v_mfma_f32_16x16x32_bf16 v[124:127], v[138:141], v[176:179], v[124:127]
	v_mfma_f32_16x16x32_bf16 v[120:123], v[152:155], v[176:179], v[120:123]
	v_mfma_f32_16x16x32_bf16 v[108:111], v[138:141], v[184:187], v[108:111]
	v_mfma_f32_16x16x32_bf16 v[104:107], v[152:155], v[184:187], v[104:107]
	v_mfma_f32_16x16x32_bf16 v[92:95], v[138:141], v[202:205], v[92:95]
	v_mfma_f32_16x16x32_bf16 v[88:91], v[152:155], v[202:205], v[88:91]
	v_mfma_f32_16x16x32_bf16 v[76:79], v[138:141], v[220:223], v[76:79]
	v_mfma_f32_16x16x32_bf16 v[72:75], v[152:155], v[220:223], v[72:75]
	v_mfma_f32_16x16x32_bf16 v[124:127], v[142:145], v[180:183], v[124:127]
	v_mfma_f32_16x16x32_bf16 v[120:123], v[156:159], v[180:183], v[120:123]
	v_mfma_f32_16x16x32_bf16 v[108:111], v[142:145], v[194:197], v[108:111]
	v_mfma_f32_16x16x32_bf16 v[104:107], v[156:159], v[194:197], v[104:107]
	v_mfma_f32_16x16x32_bf16 v[92:95], v[142:145], v[216:219], v[92:95]
	v_mfma_f32_16x16x32_bf16 v[88:91], v[156:159], v[216:219], v[88:91]
	v_mfma_f32_16x16x32_bf16 v[76:79], v[142:145], v[224:227], v[76:79]
	v_mfma_f32_16x16x32_bf16 v[72:75], v[156:159], v[224:227], v[72:75]
	s_setprio 0
	s_setprio 1
	v_mfma_f32_16x16x32_bf16 v[116:119], v[160:163], v[176:179], v[116:119]
	v_mfma_f32_16x16x32_bf16 v[112:115], v[168:171], v[176:179], v[112:115]
	v_mfma_f32_16x16x32_bf16 v[100:103], v[160:163], v[184:187], v[100:103]
	v_mfma_f32_16x16x32_bf16 v[96:99], v[168:171], v[184:187], v[96:99]
	v_mfma_f32_16x16x32_bf16 v[84:87], v[160:163], v[202:205], v[84:87]
	v_mfma_f32_16x16x32_bf16 v[80:83], v[168:171], v[202:205], v[80:83]
	v_mfma_f32_16x16x32_bf16 v[68:71], v[160:163], v[220:223], v[68:71]
	v_mfma_f32_16x16x32_bf16 v[64:67], v[168:171], v[220:223], v[64:67]
	v_mfma_f32_16x16x32_bf16 v[116:119], v[164:167], v[180:183], v[116:119]
	v_mfma_f32_16x16x32_bf16 v[112:115], v[172:175], v[180:183], v[112:115]
	v_mfma_f32_16x16x32_bf16 v[100:103], v[164:167], v[194:197], v[100:103]
	v_mfma_f32_16x16x32_bf16 v[96:99], v[172:175], v[194:197], v[96:99]
	v_mfma_f32_16x16x32_bf16 v[84:87], v[164:167], v[216:219], v[84:87]
	v_mfma_f32_16x16x32_bf16 v[80:83], v[172:175], v[216:219], v[80:83]
	v_mfma_f32_16x16x32_bf16 v[68:71], v[164:167], v[224:227], v[68:71]
	v_mfma_f32_16x16x32_bf16 v[64:67], v[172:175], v[224:227], v[64:67]
	s_setprio 0
	s_barrier
	s_add_i32 s86, s86, s54
	v_lshl_add_u64 v[146:147], s[48:49], 0, v[188:189]
	s_mov_b32 m0, s86
	ds_read_b128 v[176:179], v151 offset:16384
	ds_read_b128 v[180:183], v151 offset:17408
	ds_read_b128 v[184:187], v151 offset:18432
	ds_read_b128 v[194:197], v151 offset:19456
	ds_read_b128 v[202:205], v151 offset:20480
	ds_read_b128 v[216:219], v151 offset:21504
	ds_read_b128 v[220:223], v151 offset:22528
	ds_read_b128 v[224:227], v151 offset:23552
	global_load_lds_dwordx4 v[146:147], off
	s_add_i32 m0, s86, 0x2000
	s_add_u32 s86, s48, 0x40000
	v_lshl_add_u64 v[228:229], s[48:49], 0, v[128:129]
	s_addc_u32 s87, s49, 0
	s_add_i32 s88, s88, s54
	global_load_lds_dwordx4 v[228:229], off
	s_mov_b32 m0, s88
	v_lshl_add_u64 v[232:233], s[50:51], 0, v[130:131]
	global_load_lds_dwordx4 v188, s[86:87]
	s_add_i32 m0, s88, 0x2000
	s_nop 0
	global_load_lds_dwordx4 v128, s[86:87]
	v_lshl_add_u64 v[230:231], s[50:51], 0, v[132:133]
	s_mov_b32 m0, s55
	s_nop 0
	global_load_lds_dwordx4 v[230:231], off
	s_mov_b32 m0, s56
	s_nop 0
	global_load_lds_dwordx4 v[232:233], off
	s_waitcnt vmcnt(8)
	s_waitcnt lgkmcnt(0)
	s_barrier
	s_setprio 1
	s_waitcnt lgkmcnt(0)
	v_mfma_f32_16x16x32_bf16 v[60:63], v[138:141], v[176:179], v[60:63]
	v_mfma_f32_16x16x32_bf16 v[56:59], v[152:155], v[176:179], v[56:59]
	v_mfma_f32_16x16x32_bf16 v[44:47], v[138:141], v[184:187], v[44:47]
	v_mfma_f32_16x16x32_bf16 v[40:43], v[152:155], v[184:187], v[40:43]
	v_mfma_f32_16x16x32_bf16 v[28:31], v[138:141], v[202:205], v[28:31]
	v_mfma_f32_16x16x32_bf16 v[24:27], v[152:155], v[202:205], v[24:27]
	v_mfma_f32_16x16x32_bf16 v[12:15], v[138:141], v[220:223], v[12:15]
	v_mfma_f32_16x16x32_bf16 v[8:11], v[152:155], v[220:223], v[8:11]
	v_mfma_f32_16x16x32_bf16 v[60:63], v[142:145], v[180:183], v[60:63]
	v_mfma_f32_16x16x32_bf16 v[56:59], v[156:159], v[180:183], v[56:59]
	v_mfma_f32_16x16x32_bf16 v[44:47], v[142:145], v[194:197], v[44:47]
	v_mfma_f32_16x16x32_bf16 v[40:43], v[156:159], v[194:197], v[40:43]
	v_mfma_f32_16x16x32_bf16 v[28:31], v[142:145], v[216:219], v[28:31]
	v_mfma_f32_16x16x32_bf16 v[24:27], v[156:159], v[216:219], v[24:27]
	v_mfma_f32_16x16x32_bf16 v[12:15], v[142:145], v[224:227], v[12:15]
	v_mfma_f32_16x16x32_bf16 v[8:11], v[156:159], v[224:227], v[8:11]
	s_setprio 0
	s_setprio 1
	v_mfma_f32_16x16x32_bf16 v[52:55], v[160:163], v[176:179], v[52:55]
	v_mfma_f32_16x16x32_bf16 v[48:51], v[168:171], v[176:179], v[48:51]
	v_mfma_f32_16x16x32_bf16 v[36:39], v[160:163], v[184:187], v[36:39]
	v_mfma_f32_16x16x32_bf16 v[32:35], v[168:171], v[184:187], v[32:35]
	v_mfma_f32_16x16x32_bf16 v[20:23], v[160:163], v[202:205], v[20:23]
	v_mfma_f32_16x16x32_bf16 v[16:19], v[168:171], v[202:205], v[16:19]
	v_mfma_f32_16x16x32_bf16 v[4:7], v[160:163], v[220:223], v[4:7]
	v_mfma_f32_16x16x32_bf16 v[0:3], v[168:171], v[220:223], v[0:3]
	v_mfma_f32_16x16x32_bf16 v[52:55], v[164:167], v[180:183], v[52:55]
	v_mfma_f32_16x16x32_bf16 v[48:51], v[172:175], v[180:183], v[48:51]
	v_mfma_f32_16x16x32_bf16 v[36:39], v[164:167], v[194:197], v[36:39]
	v_mfma_f32_16x16x32_bf16 v[32:35], v[172:175], v[194:197], v[32:35]
	v_mfma_f32_16x16x32_bf16 v[20:23], v[164:167], v[216:219], v[20:23]
	v_mfma_f32_16x16x32_bf16 v[16:19], v[172:175], v[216:219], v[16:19]
	v_mfma_f32_16x16x32_bf16 v[4:7], v[164:167], v[224:227], v[4:7]
	v_mfma_f32_16x16x32_bf16 v[0:3], v[172:175], v[224:227], v[0:3]
	s_setprio 0
	s_barrier
	s_add_i32 s86, 0, 0x18000
	s_add_i32 s87, 0, 0x1c000
	v_add_u32_e32 v156, s86, v150
	v_add_u32_e32 v172, s87, v150
	ds_read_b128 v[138:141], v156
	ds_read_b128 v[142:145], v156 offset:1024
	ds_read_b128 v[152:155], v156 offset:2048
	ds_read_b128 v[156:159], v156 offset:3072
	ds_read_b128 v[160:163], v172
	ds_read_b128 v[164:167], v172 offset:1024
	ds_read_b128 v[168:171], v172 offset:2048
	ds_read_b128 v[172:175], v172 offset:3072
	s_add_u32 s50, s50, 0x40000
	s_addc_u32 s51, s51, 0
	s_mov_b32 m0, s57
	ds_read_b128 v[176:179], v151 offset:32768
	ds_read_b128 v[180:183], v151 offset:33792
	ds_read_b128 v[184:187], v151 offset:34816
	ds_read_b128 v[194:197], v151 offset:35840
	ds_read_b128 v[202:205], v151 offset:36864
	ds_read_b128 v[216:219], v151 offset:37888
	ds_read_b128 v[220:223], v151 offset:38912
	ds_read_b128 v[224:227], v151 offset:39936
	global_load_lds_dwordx4 v132, s[50:51]
	s_mov_b32 m0, s58
	s_nop 0
	global_load_lds_dwordx4 v130, s[50:51]
	s_waitcnt vmcnt(8)
	s_waitcnt lgkmcnt(0)
	s_barrier
	s_setprio 1
	s_waitcnt lgkmcnt(0)
	v_mfma_f32_16x16x32_bf16 v[124:127], v[138:141], v[176:179], v[124:127]
	v_mfma_f32_16x16x32_bf16 v[120:123], v[152:155], v[176:179], v[120:123]
	v_mfma_f32_16x16x32_bf16 v[108:111], v[138:141], v[184:187], v[108:111]
	v_mfma_f32_16x16x32_bf16 v[104:107], v[152:155], v[184:187], v[104:107]
	v_mfma_f32_16x16x32_bf16 v[92:95], v[138:141], v[202:205], v[92:95]
	v_mfma_f32_16x16x32_bf16 v[88:91], v[152:155], v[202:205], v[88:91]
	v_mfma_f32_16x16x32_bf16 v[76:79], v[138:141], v[220:223], v[76:79]
	v_mfma_f32_16x16x32_bf16 v[72:75], v[152:155], v[220:223], v[72:75]
	v_mfma_f32_16x16x32_bf16 v[124:127], v[142:145], v[180:183], v[124:127]
	v_mfma_f32_16x16x32_bf16 v[120:123], v[156:159], v[180:183], v[120:123]
	v_mfma_f32_16x16x32_bf16 v[108:111], v[142:145], v[194:197], v[108:111]
	v_mfma_f32_16x16x32_bf16 v[104:107], v[156:159], v[194:197], v[104:107]
	v_mfma_f32_16x16x32_bf16 v[92:95], v[142:145], v[216:219], v[92:95]
	v_mfma_f32_16x16x32_bf16 v[88:91], v[156:159], v[216:219], v[88:91]
	v_mfma_f32_16x16x32_bf16 v[76:79], v[142:145], v[224:227], v[76:79]
	v_mfma_f32_16x16x32_bf16 v[72:75], v[156:159], v[224:227], v[72:75]
	s_setprio 0
	s_setprio 1
	v_mfma_f32_16x16x32_bf16 v[116:119], v[160:163], v[176:179], v[116:119]
	v_mfma_f32_16x16x32_bf16 v[112:115], v[168:171], v[176:179], v[112:115]
	v_mfma_f32_16x16x32_bf16 v[100:103], v[160:163], v[184:187], v[100:103]
	v_mfma_f32_16x16x32_bf16 v[96:99], v[168:171], v[184:187], v[96:99]
	v_mfma_f32_16x16x32_bf16 v[84:87], v[160:163], v[202:205], v[84:87]
	v_mfma_f32_16x16x32_bf16 v[80:83], v[168:171], v[202:205], v[80:83]
	v_mfma_f32_16x16x32_bf16 v[68:71], v[160:163], v[220:223], v[68:71]
	v_mfma_f32_16x16x32_bf16 v[64:67], v[168:171], v[220:223], v[64:67]
	v_mfma_f32_16x16x32_bf16 v[116:119], v[164:167], v[180:183], v[116:119]
	v_mfma_f32_16x16x32_bf16 v[112:115], v[172:175], v[180:183], v[112:115]
	v_mfma_f32_16x16x32_bf16 v[100:103], v[164:167], v[194:197], v[100:103]
	v_mfma_f32_16x16x32_bf16 v[96:99], v[172:175], v[194:197], v[96:99]
	v_mfma_f32_16x16x32_bf16 v[84:87], v[164:167], v[216:219], v[84:87]
	v_mfma_f32_16x16x32_bf16 v[80:83], v[172:175], v[216:219], v[80:83]
	v_mfma_f32_16x16x32_bf16 v[68:71], v[164:167], v[224:227], v[68:71]
	v_mfma_f32_16x16x32_bf16 v[64:67], v[172:175], v[224:227], v[64:67]
	s_setprio 0
	s_barrier
	s_add_i32 s50, s86, s54
	v_lshl_add_u64 v[146:147], v[146:147], 0, s[62:63]
	s_mov_b32 m0, s50
	ds_read_b128 v[176:179], v151 offset:49152
	ds_read_b128 v[180:183], v151 offset:50176
	ds_read_b128 v[184:187], v151 offset:51200
	ds_read_b128 v[194:197], v151 offset:52224
	ds_read_b128 v[202:205], v151 offset:53248
	ds_read_b128 v[216:219], v151 offset:54272
	ds_read_b128 v[220:223], v151 offset:55296
	ds_read_b128 v[224:227], v151 offset:56320
	global_load_lds_dwordx4 v[146:147], off
	s_add_i32 m0, s50, 0x2000
	s_add_u32 s48, s48, 0x40080
	v_lshl_add_u64 v[146:147], v[228:229], 0, s[62:63]
	s_addc_u32 s49, s49, 0
	s_add_i32 s50, s87, s54
	global_load_lds_dwordx4 v[146:147], off
	s_mov_b32 m0, s50
	s_nop 0
	global_load_lds_dwordx4 v188, s[48:49]
	s_add_i32 m0, s50, 0x2000
	s_nop 0
	global_load_lds_dwordx4 v128, s[48:49]
	v_lshl_add_u64 v[146:147], v[230:231], 0, s[62:63]
	s_mov_b32 m0, s67
	s_nop 0
	global_load_lds_dwordx4 v[146:147], off
	v_lshl_add_u64 v[146:147], v[232:233], 0, s[62:63]
	s_mov_b32 m0, s69
	s_nop 0
	global_load_lds_dwordx4 v[146:147], off
	s_waitcnt vmcnt(8)
	s_waitcnt lgkmcnt(0)
	s_barrier
	s_setprio 1
	s_waitcnt lgkmcnt(0)
	v_mfma_f32_16x16x32_bf16 v[60:63], v[138:141], v[176:179], v[60:63]
	v_mfma_f32_16x16x32_bf16 v[56:59], v[152:155], v[176:179], v[56:59]
	v_mfma_f32_16x16x32_bf16 v[44:47], v[138:141], v[184:187], v[44:47]
	v_mfma_f32_16x16x32_bf16 v[40:43], v[152:155], v[184:187], v[40:43]
	v_mfma_f32_16x16x32_bf16 v[28:31], v[138:141], v[202:205], v[28:31]
	v_mfma_f32_16x16x32_bf16 v[24:27], v[152:155], v[202:205], v[24:27]
	v_mfma_f32_16x16x32_bf16 v[12:15], v[138:141], v[220:223], v[12:15]
	v_mfma_f32_16x16x32_bf16 v[8:11], v[152:155], v[220:223], v[8:11]
	v_mfma_f32_16x16x32_bf16 v[60:63], v[142:145], v[180:183], v[60:63]
	v_mfma_f32_16x16x32_bf16 v[56:59], v[156:159], v[180:183], v[56:59]
	v_mfma_f32_16x16x32_bf16 v[44:47], v[142:145], v[194:197], v[44:47]
	v_mfma_f32_16x16x32_bf16 v[40:43], v[156:159], v[194:197], v[40:43]
	v_mfma_f32_16x16x32_bf16 v[28:31], v[142:145], v[216:219], v[28:31]
	v_mfma_f32_16x16x32_bf16 v[24:27], v[156:159], v[216:219], v[24:27]
	v_mfma_f32_16x16x32_bf16 v[12:15], v[142:145], v[224:227], v[12:15]
	v_mfma_f32_16x16x32_bf16 v[8:11], v[156:159], v[224:227], v[8:11]
	s_setprio 0
	s_setprio 1
	v_mfma_f32_16x16x32_bf16 v[52:55], v[160:163], v[176:179], v[52:55]
	v_mfma_f32_16x16x32_bf16 v[48:51], v[168:171], v[176:179], v[48:51]
	v_mfma_f32_16x16x32_bf16 v[36:39], v[160:163], v[184:187], v[36:39]
	v_mfma_f32_16x16x32_bf16 v[32:35], v[168:171], v[184:187], v[32:35]
	v_mfma_f32_16x16x32_bf16 v[20:23], v[160:163], v[202:205], v[20:23]
	v_mfma_f32_16x16x32_bf16 v[16:19], v[168:171], v[202:205], v[16:19]
	v_mfma_f32_16x16x32_bf16 v[4:7], v[160:163], v[220:223], v[4:7]
	v_mfma_f32_16x16x32_bf16 v[0:3], v[168:171], v[220:223], v[0:3]
	v_mfma_f32_16x16x32_bf16 v[52:55], v[164:167], v[180:183], v[52:55]
	v_mfma_f32_16x16x32_bf16 v[48:51], v[172:175], v[180:183], v[48:51]
	v_mfma_f32_16x16x32_bf16 v[36:39], v[164:167], v[194:197], v[36:39]
	v_mfma_f32_16x16x32_bf16 v[32:35], v[172:175], v[194:197], v[32:35]
	v_mfma_f32_16x16x32_bf16 v[20:23], v[164:167], v[216:219], v[20:23]
	v_mfma_f32_16x16x32_bf16 v[16:19], v[172:175], v[216:219], v[16:19]
	v_mfma_f32_16x16x32_bf16 v[4:7], v[164:167], v[224:227], v[4:7]
	v_mfma_f32_16x16x32_bf16 v[0:3], v[172:175], v[224:227], v[0:3]
	s_setprio 0
	s_barrier
	s_add_u32 s38, s38, 0x100
	s_addc_u32 s39, s39, 0
	s_add_u32 s83, s83, 0x100
	s_addc_u32 s84, s84, 0
	s_cmp_ge_i32 s85, s60
	s_mov_b32 s48, s85
	s_cbranch_scc0 .LBB0_734
	s_mov_b64 s[88:89], 0x8000
